# add LDS-DMA K-loop for out-proj (ph5, A-fragment rms scaling kept bit-exact), rewritten EPI_OUT and batched EPI_BF16 epilogues
# speedup vs baseline: 1.1925x; 1.0174x over previous
; template <int HOOK>
; __device__ __forceinline__ void gemm_tile(const u16* __restrict__ A, int lda, const u16* __restrict__ B, int ldb, int K, char* smem, const float* ssq = nullptr) {
;     ...
;   u16* sA = (u16*)smem;
;   u16* sB = sA + 128 * 72;
;   const int tid = (threadIdx.x + zz), lane = tid & 63, wave = tid >> 6;
;   const int wm = (wave >> 1) * 64, wn = (wave & 1) * 64;
;   const int lr = lane & 15, lq = lane >> 4;
;   f32x4 acc[4][4];
; #pragma unroll
;   for (int i = 0; i < 4; i++)
; #pragma unroll
;     for (int j = 0; j < 4; j++) acc[i][j] = (f32x4){0.f, 0.f, 0.f, 0.f};
;   u32x4 ra[4], rb[4];
;   float rs[4];
;   if (HOOK) {
; #pragma unroll
;     for (int i = 0; i < 4; i++) {
;       int row = (tid + i * NTHR) >> 3;
;       float4 q = *(const float4*)(ssq + (size_t)row * 4);
;       rs[i] = rsqrtf((q.x + q.y + q.z + q.w) * (1.f / 256.f) + 1e-6f);
;     }
;   }
; #pragma unroll
;   for (int i = 0; i < 4; i++) {
;     int id = tid + i * NTHR; int row = id >> 3, ch = id & 7;
;     ra[i] = *(const u32x4*)(A + (size_t)row * lda + ch * 8);
;     rb[i] = *(const u32x4*)(B + (size_t)row * ldb + ch * 8);
;   }
; #pragma unroll 1
;   for (int k0 = 0; k0 < K; k0 += 64) {
;     __syncthreads();
;     ...
;     int mt = t / ntiles, nt = t % ntiles;
;     int m0 = mt * 128, n0 = nt * 128;
;     gemm_tile<(EPI == EPI_OUT) ? 1 : 0>(A + (size_t)m0 * lda, lda, Bt + (size_t)n0 * ldb, ldb, K, smem, (const float*)(p.ws + zz + O_SSQ) + (size_t)m0 * 4);
.LBB0_778:
	s_ashr_i32 s0, s11, 31
	s_lshr_b32 s0, s0, 28
	s_add_i32 s0, s11, s0
	s_and_b32 s1, s0, 0x1fffff0
	s_lshl_b32 s0, s0, 3
	s_and_b32 s2, s0, 0xffffff80
	s_sub_i32 s1, s11, s1
	s_ashr_i32 s3, s2, 31
	s_lshl_b32 s6, s1, 7
	s_lshl_b64 s[0:1], s[2:3], 11
	s_add_u32 s8, s12, s0
	s_addc_u32 s9, s13, s1
	s_ashr_i32 s7, s6, 31
	s_mov_b32 s3, 0
	s_lshl_b64 s[24:25], s[6:7], 11
	v_add_u32_e32 v122, s3, v128
	s_waitcnt vmcnt(3)
	v_add_u32_e32 v8, 0x100, v122
	s_waitcnt vmcnt(2)
	v_add_u32_e32 v16, 0x200, v122
	s_waitcnt vmcnt(0)
	v_add_u32_e32 v28, 0x300, v122
	s_add_u32 s26, s14, s24
	v_lshlrev_b32_e32 v0, 4, v122
	v_ashrrev_i32_e32 v36, 3, v122
	v_ashrrev_i32_e32 v40, 3, v8
	s_waitcnt vmcnt(0)
	v_ashrrev_i32_e32 v44, 3, v16
	v_ashrrev_i32_e32 v48, 3, v28
	s_addc_u32 s27, s15, s25
	v_and_b32_e32 v132, 0x70, v0
	v_ashrrev_i32_e32 v37, 31, v36
	v_ashrrev_i32_e32 v41, 31, v40
	v_ashrrev_i32_e32 v45, 31, v44
	v_ashrrev_i32_e32 v49, 31, v48
	v_lshl_add_u64 v[24:25], s[8:9], 0, v[132:133]
	v_lshl_add_u64 v[26:27], s[26:27], 0, v[132:133]
	v_lshlrev_b64 v[38:39], 11, v[36:37]
	v_lshlrev_b64 v[42:43], 11, v[40:41]
	v_lshlrev_b64 v[46:47], 11, v[44:45]
	v_lshlrev_b64 v[50:51], 11, v[48:49]
	v_lshl_add_u64 v[0:1], v[24:25], 0, v[38:39]
	v_lshl_add_u64 v[4:5], v[26:27], 0, v[38:39]
	v_lshl_add_u64 v[8:9], v[24:25], 0, v[42:43]
	v_lshl_add_u64 v[12:13], v[26:27], 0, v[42:43]
	v_lshl_add_u64 v[16:17], v[24:25], 0, v[46:47]
	v_lshl_add_u64 v[20:21], v[26:27], 0, v[46:47]
	v_lshl_add_u64 v[24:25], v[24:25], 0, v[50:51]
	v_lshl_add_u64 v[26:27], v[26:27], 0, v[50:51]
	v_ashrrev_i32_e32 v52, 1, v122
	v_and_b32_e32 v123, 15, v122
	v_and_b32_e32 v124, 0xffffffc0, v52
	s_add_u32 s0, s19, s0
	v_or_b32_e32 v24, v124, v123
	s_addc_u32 s1, s20, s1
	v_bfe_u32 v125, v122, 4, 2
	v_and_b32_e32 v26, 0x4f, v122
	v_mul_lo_u32 v27, v24, s33
	v_and_b32_e32 v24, 7, v122
	v_lshl_add_u64 v[104:105], s[0:1], 0, v[38:39]
	v_lshl_add_u64 v[106:107], s[0:1], 0, v[42:43]
	v_lshl_add_u64 v[108:109], s[0:1], 0, v[46:47]
	v_lshl_add_u64 v[110:111], s[0:1], 0, v[50:51]
	s_add_u32 s0, s21, s24
	v_lshlrev_b32_e32 v25, 4, v125
	v_mad_u64_u32 v[96:97], s[8:9], v36, s33, v[132:133]
	v_mad_u64_u32 v[98:99], s[8:9], v40, s33, v[132:133]
	v_mad_u64_u32 v[100:101], s[8:9], v44, s33, v[132:133]
	v_mad_u64_u32 v[102:103], s[8:9], v48, s33, v[132:133]
	v_mul_u32_u24_e32 v26, 0x90, v26
	v_lshlrev_b32_e32 v132, 4, v24
	s_addc_u32 s1, s22, s25
	v_mov_b32_e32 v24, 0
	v_lshl_add_u64 v[112:113], s[0:1], 0, v[38:39]
	v_lshl_add_u64 v[114:115], s[0:1], 0, v[42:43]
	v_lshl_add_u64 v[116:117], s[0:1], 0, v[46:47]
	v_lshl_add_u64 v[118:119], s[0:1], 0, v[50:51]
	s_mov_b32 s3, 0
	v_add_u32_e32 v97, v25, v27
	v_add_u32_e32 v99, v25, v26
	v_mov_b32_e32 v25, v24
	v_mov_b32_e32 v26, v24
	v_mov_b32_e32 v27, v24
	v_mov_b32_e32 v36, v24
	v_mov_b32_e32 v37, v24
	v_mov_b32_e32 v38, v24
	v_mov_b32_e32 v39, v24
	v_mov_b32_e32 v40, v24
	v_mov_b32_e32 v41, v24
	v_mov_b32_e32 v42, v24
	v_mov_b32_e32 v43, v24
	v_mov_b32_e32 v44, v24
	v_mov_b32_e32 v45, v24
	v_mov_b32_e32 v46, v24
	v_mov_b32_e32 v47, v24
	v_mov_b32_e32 v48, v24
	v_mov_b32_e32 v49, v24
	v_mov_b32_e32 v50, v24
	v_mov_b32_e32 v51, v24
	v_mov_b32_e32 v52, v24
	v_mov_b32_e32 v53, v24
	v_mov_b32_e32 v54, v24
	v_mov_b32_e32 v55, v24
	v_mov_b32_e32 v56, v24
	v_mov_b32_e32 v57, v24
	v_mov_b32_e32 v58, v24
	v_mov_b32_e32 v59, v24
	v_mov_b32_e32 v60, v24
	v_mov_b32_e32 v61, v24
	v_mov_b32_e32 v62, v24
	v_mov_b32_e32 v63, v24
	v_mov_b32_e32 v64, v24
	v_mov_b32_e32 v65, v24
	v_mov_b32_e32 v66, v24
	v_mov_b32_e32 v67, v24
	v_mov_b32_e32 v68, v24
	v_mov_b32_e32 v69, v24
	v_mov_b32_e32 v70, v24
	v_mov_b32_e32 v71, v24
	v_mov_b32_e32 v72, v24
	v_mov_b32_e32 v73, v24
	v_mov_b32_e32 v74, v24
	v_mov_b32_e32 v75, v24
	v_mov_b32_e32 v76, v24
	v_mov_b32_e32 v77, v24
	v_mov_b32_e32 v78, v24
	v_mov_b32_e32 v79, v24
	v_mov_b32_e32 v80, v24
	v_mov_b32_e32 v81, v24
	v_mov_b32_e32 v82, v24
	v_mov_b32_e32 v83, v24
	v_mov_b32_e32 v84, v24
	v_mov_b32_e32 v85, v24
	v_mov_b32_e32 v86, v24
	v_mov_b32_e32 v87, v24
	v_mov_b32_e32 v88, v24
	v_mov_b32_e32 v89, v24
	v_mov_b32_e32 v90, v24
	v_mov_b32_e32 v91, v24
	v_mov_b32_e32 v92, v24
	v_mov_b32_e32 v93, v24
	v_mov_b32_e32 v94, v24
	v_mov_b32_e32 v95, v24
	v_lshrrev_b32_e32 v208, 3, v122
	v_xor_b32_e32 v208, v208, v122
	v_and_b32_e32 v208, 7, v208
	v_lshlrev_b32_e32 v208, 4, v208
	v_add_u32_e32 v208, 0xffffff80, v208
	v_mov_b32_e32 v209, -1
	v_lshl_add_u64 v[104:105], v[104:105], 0, v[208:209]
	v_lshl_add_u64 v[106:107], v[106:107], 0, v[208:209]
	v_lshl_add_u64 v[108:109], v[108:109], 0, v[208:209]
	v_lshl_add_u64 v[110:111], v[110:111], 0, v[208:209]
	v_lshl_add_u64 v[112:113], v[112:113], 0, v[208:209]
	v_lshl_add_u64 v[114:115], v[114:115], 0, v[208:209]
	v_lshl_add_u64 v[116:117], v[116:117], 0, v[208:209]
	v_lshl_add_u64 v[118:119], v[118:119], 0, v[208:209]
	v_lshrrev_b32_e32 v208, 6, v122
	s_nop 1
	v_readfirstlane_b32 s56, v208
	s_nop 3
	s_lshl_b32 s56, s56, 10
	s_waitcnt lgkmcnt(0)
	s_barrier
	s_mov_b32 m0, s56
	s_nop 0
	global_load_lds_dwordx4 v[104:105], off
	s_add_u32 m0, s56, 0x1000
	s_nop 0
	global_load_lds_dwordx4 v[106:107], off
	s_add_u32 m0, s56, 0x2000
	s_nop 0
	global_load_lds_dwordx4 v[108:109], off
	s_add_u32 m0, s56, 0x3000
	s_nop 0
	global_load_lds_dwordx4 v[110:111], off
	s_add_u32 m0, s56, 0x4000
	s_nop 0
	global_load_lds_dwordx4 v[112:113], off
	s_add_u32 m0, s56, 0x5000
	s_nop 0
	global_load_lds_dwordx4 v[114:115], off
	s_add_u32 m0, s56, 0x6000
	s_nop 0
	global_load_lds_dwordx4 v[116:117], off
	s_add_u32 m0, s56, 0x7000
	s_nop 0
	global_load_lds_dwordx4 v[118:119], off
	v_lshl_add_u64 v[104:105], v[104:105], 0, s[30:31]
	v_lshl_add_u64 v[106:107], v[106:107], 0, s[30:31]
	v_lshl_add_u64 v[108:109], v[108:109], 0, s[30:31]
	v_lshl_add_u64 v[110:111], v[110:111], 0, s[30:31]
	v_lshl_add_u64 v[112:113], v[112:113], 0, s[30:31]
	v_lshl_add_u64 v[114:115], v[114:115], 0, s[30:31]
	v_lshl_add_u64 v[116:117], v[116:117], 0, s[30:31]
	v_lshl_add_u64 v[118:119], v[118:119], 0, s[30:31]
	v_and_b32_e32 v204, 7, v123
	v_xor_b32_e32 v204, v204, v125
	v_lshlrev_b32_e32 v204, 4, v204
	v_or_b32_e32 v206, v124, v123
	v_lshl_add_u32 v205, v206, 7, v204
	v_and_b32_e32 v206, 0x4f, v122
	v_lshl_add_u32 v206, v206, 7, v204
	v_xor_b32_e32 v207, 64, v206
	v_xor_b32_e32 v204, 64, v205
	s_waitcnt vmcnt(0)
	s_barrier

; template <int HOOK>
; __device__ __forceinline__ void gemm_tile(const u16* __restrict__ A, int lda, const u16* __restrict__ B, int ldb, int K, char* smem, const float* ssq = nullptr) {
;     ...
;   __syncthreads();
;   float* sC = (float*)smem;
; #pragma unroll
;   for (int i = 0; i < 4; i++)
; #pragma unroll
;     for (int j = 0; j < 4; j++)
; #pragma unroll
;       for (int r = 0; r < 4; r++) sC[(wm + i * 16 + lq * 4 + r) * 128 + wn + j * 16 + lr] = acc[i][j][r];
;   __syncthreads();
;     ...
;     if (EPI == EPI_BF16) {
;       u16* out = (u16*)outp;
;       for (int i = tid; i < 128 * 32; i += NTHR) {
;         int r = i >> 5, c4 = (i & 31) * 4;
;         float4 v = *(const float4*)(sC + r * 128 + c4);
;         uint2 o; o.x = pack2(v.x, v.y); o.y = pack2(v.z, v.w);
;         *(uint2*)(out + (size_t)(m0 + r) * ldo + n0 + c4) = o;
;       }
.LBB0_782:
	s_waitcnt vmcnt(7)
	v_lshlrev_b32_e32 v1, 9, v124
	v_and_or_b32 v0, v122, 64, v123
	v_lshl_or_b32 v1, v125, 11, v1
	v_lshl_or_b32 v0, v0, 2, v1
	v_add_u32_e32 v1, 0x400, v0
	s_barrier
	ds_write2_b32 v0, v92, v88 offset1:16
	ds_write2_b32 v0, v93, v89 offset0:128 offset1:144
	ds_write2_b32 v1, v94, v90 offset1:16
	ds_write2_b32 v1, v95, v91 offset0:128 offset1:144
	ds_write2_b32 v0, v84, v80 offset0:32 offset1:48
	ds_write2_b32 v0, v85, v81 offset0:160 offset1:176
	ds_write2_b32 v1, v86, v82 offset0:32 offset1:48
	ds_write2_b32 v1, v87, v83 offset0:160 offset1:176
	v_add_u32_e32 v1, 0x2000, v0
	v_add_u32_e32 v2, 0x2400, v0
	ds_write2_b32 v1, v76, v72 offset1:16
	ds_write2_b32 v1, v77, v73 offset0:128 offset1:144
	ds_write2_b32 v2, v78, v74 offset1:16
	ds_write2_b32 v2, v79, v75 offset0:128 offset1:144
	ds_write2_b32 v1, v68, v64 offset0:32 offset1:48
	ds_write2_b32 v1, v69, v65 offset0:160 offset1:176
	ds_write2_b32 v2, v70, v66 offset0:32 offset1:48
	ds_write2_b32 v2, v71, v67 offset0:160 offset1:176
	v_add_u32_e32 v1, 0x4000, v0
	v_add_u32_e32 v2, 0x4400, v0
	ds_write2_b32 v1, v60, v56 offset1:16
	ds_write2_b32 v1, v61, v57 offset0:128 offset1:144
	ds_write2_b32 v2, v62, v58 offset1:16
	ds_write2_b32 v2, v63, v59 offset0:128 offset1:144
	ds_write2_b32 v1, v52, v48 offset0:32 offset1:48
	ds_write2_b32 v1, v53, v49 offset0:160 offset1:176
	ds_write2_b32 v2, v54, v50 offset0:32 offset1:48
	ds_write2_b32 v2, v55, v51 offset0:160 offset1:176
	v_add_u32_e32 v1, 0x6000, v0
	v_add_u32_e32 v0, 0x6400, v0
	ds_write2_b32 v1, v44, v40 offset1:16
	ds_write2_b32 v1, v45, v41 offset0:128 offset1:144
	ds_write2_b32 v0, v46, v42 offset1:16
	ds_write2_b32 v0, v47, v43 offset0:128 offset1:144
	ds_write2_b32 v1, v36, v24 offset0:32 offset1:48
	ds_write2_b32 v1, v37, v25 offset0:160 offset1:176
	ds_write2_b32 v0, v38, v26 offset0:32 offset1:48
	ds_write2_b32 v0, v39, v27 offset0:160 offset1:176
	s_waitcnt lgkmcnt(0)
	s_barrier
	s_and_saveexec_b64 s[0:1], s[4:5]
	s_movk_i32 s3, 0xeff
	s_cbranch_execz .LBB0_777
	s_lshl_b64 s[6:7], s[6:7], 1
	s_add_u32 s6, s16, s6
	s_addc_u32 s7, s17, s7
	v_lshrrev_b32_e32 v6, 5, v120
	v_and_b32_e32 v7, 31, v120
	v_lshlrev_b32_e32 v0, 4, v7
	v_lshl_or_b32 v0, v6, 9, v0
	v_add_u32_e32 v6, s2, v6
	v_lshlrev_b32_e32 v6, 12, v6
	v_lshl_add_u32 v1, v7, 3, v6
	ds_read_b128 v[8:11], v0 offset:0
	ds_read_b128 v[12:15], v0 offset:4096
	ds_read_b128 v[16:19], v0 offset:8192
	ds_read_b128 v[20:23], v0 offset:12288
	ds_read_b128 v[24:27], v0 offset:16384
	ds_read_b128 v[28:31], v0 offset:20480
	ds_read_b128 v[32:35], v0 offset:24576
	ds_read_b128 v[36:39], v0 offset:28672
	s_waitcnt lgkmcnt(7)
	v_cvt_pk_bf16_f32 v8, v8, v9
	v_cvt_pk_bf16_f32 v9, v10, v11
	global_store_dwordx2 v1, v[8:9], s[6:7]
	v_add_u32_e32 v1, 0x8000, v1
	ds_read_b128 v[40:43], v0 offset:32768
	s_waitcnt lgkmcnt(7)
	v_cvt_pk_bf16_f32 v12, v12, v13
	v_cvt_pk_bf16_f32 v13, v14, v15
	global_store_dwordx2 v1, v[12:13], s[6:7]
	v_add_u32_e32 v1, 0x8000, v1
	ds_read_b128 v[44:47], v0 offset:36864
	s_waitcnt lgkmcnt(7)
	v_cvt_pk_bf16_f32 v16, v16, v17
	v_cvt_pk_bf16_f32 v17, v18, v19
	global_store_dwordx2 v1, v[16:17], s[6:7]
	v_add_u32_e32 v1, 0x8000, v1
	ds_read_b128 v[48:51], v0 offset:40960
	s_waitcnt lgkmcnt(7)
	v_cvt_pk_bf16_f32 v20, v20, v21
	v_cvt_pk_bf16_f32 v21, v22, v23
	global_store_dwordx2 v1, v[20:21], s[6:7]
	v_add_u32_e32 v1, 0x8000, v1
	ds_read_b128 v[52:55], v0 offset:45056
	s_waitcnt lgkmcnt(7)
	v_cvt_pk_bf16_f32 v24, v24, v25
	v_cvt_pk_bf16_f32 v25, v26, v27
	global_store_dwordx2 v1, v[24:25], s[6:7]
	v_add_u32_e32 v1, 0x8000, v1
	ds_read_b128 v[56:59], v0 offset:49152
	s_waitcnt lgkmcnt(7)
	v_cvt_pk_bf16_f32 v28, v28, v29
	v_cvt_pk_bf16_f32 v29, v30, v31
	global_store_dwordx2 v1, v[28:29], s[6:7]
	v_add_u32_e32 v1, 0x8000, v1
	ds_read_b128 v[60:63], v0 offset:53248
	s_waitcnt lgkmcnt(7)
	v_cvt_pk_bf16_f32 v32, v32, v33
	v_cvt_pk_bf16_f32 v33, v34, v35
	global_store_dwordx2 v1, v[32:33], s[6:7]
	v_add_u32_e32 v1, 0x8000, v1
	ds_read_b128 v[64:67], v0 offset:57344
	s_waitcnt lgkmcnt(7)
	v_cvt_pk_bf16_f32 v36, v36, v37
	v_cvt_pk_bf16_f32 v37, v38, v39
	global_store_dwordx2 v1, v[36:37], s[6:7]
	v_add_u32_e32 v1, 0x8000, v1
	ds_read_b128 v[68:71], v0 offset:61440
	s_waitcnt lgkmcnt(7)
	v_cvt_pk_bf16_f32 v40, v40, v41
	v_cvt_pk_bf16_f32 v41, v42, v43
	global_store_dwordx2 v1, v[40:41], s[6:7]
	v_add_u32_e32 v1, 0x8000, v1
	s_waitcnt lgkmcnt(6)
	v_cvt_pk_bf16_f32 v44, v44, v45
	v_cvt_pk_bf16_f32 v45, v46, v47
	global_store_dwordx2 v1, v[44:45], s[6:7]
	v_add_u32_e32 v1, 0x8000, v1
	s_waitcnt lgkmcnt(5)
	v_cvt_pk_bf16_f32 v48, v48, v49
	v_cvt_pk_bf16_f32 v49, v50, v51
	global_store_dwordx2 v1, v[48:49], s[6:7]
	v_add_u32_e32 v1, 0x8000, v1
	s_waitcnt lgkmcnt(4)
	v_cvt_pk_bf16_f32 v52, v52, v53
	v_cvt_pk_bf16_f32 v53, v54, v55
	global_store_dwordx2 v1, v[52:53], s[6:7]
	v_add_u32_e32 v1, 0x8000, v1
	s_waitcnt lgkmcnt(3)
	v_cvt_pk_bf16_f32 v56, v56, v57
	v_cvt_pk_bf16_f32 v57, v58, v59
	global_store_dwordx2 v1, v[56:57], s[6:7]
	v_add_u32_e32 v1, 0x8000, v1
	s_waitcnt lgkmcnt(2)
	v_cvt_pk_bf16_f32 v60, v60, v61
	v_cvt_pk_bf16_f32 v61, v62, v63
	global_store_dwordx2 v1, v[60:61], s[6:7]
	v_add_u32_e32 v1, 0x8000, v1
	s_waitcnt lgkmcnt(1)
	v_cvt_pk_bf16_f32 v64, v64, v65
	v_cvt_pk_bf16_f32 v65, v66, v67
	global_store_dwordx2 v1, v[64:65], s[6:7]
	v_add_u32_e32 v1, 0x8000, v1
	s_waitcnt lgkmcnt(0)
	v_cvt_pk_bf16_f32 v68, v68, v69
	v_cvt_pk_bf16_f32 v69, v70, v71
	global_store_dwordx2 v1, v[68:69], s[6:7]
	s_branch .LBB0_777

; template <int HOOK>
; __device__ __forceinline__ void gemm_tile(const u16* __restrict__ A, int lda, const u16* __restrict__ B, int ldb, int K, char* smem, const float* ssq = nullptr) {
;     ...
;   if (HOOK) {
; #pragma unroll
;     for (int i = 0; i < 4; i++) {
;       int row = (tid + i * NTHR) >> 3;
;       float4 q = *(const float4*)(ssq + (size_t)row * 4);
;       rs[i] = rsqrtf((q.x + q.y + q.z + q.w) * (1.f / 256.f) + 1e-6f);
;     }
;   }
; #pragma unroll
;   for (int i = 0; i < 4; i++) {
;     int id = tid + i * NTHR; int row = id >> 3, ch = id & 7;
;     ra[i] = *(const u32x4*)(A + (size_t)row * lda + ch * 8);
;     rb[i] = *(const u32x4*)(B + (size_t)row * ldb + ch * 8);
;   }
;     ...
;     int mt = t / ntiles, nt = t % ntiles;
;     int m0 = mt * 128, n0 = nt * 128;
;     gemm_tile<(EPI == EPI_OUT) ? 1 : 0>(A + (size_t)m0 * lda, lda, Bt + (size_t)n0 * ldb, ldb, K, smem, (const float*)(p.ws + zz + O_SSQ) + (size_t)m0 * 4);
.LBB0_805:
	s_ashr_i32 s0, s19, 31
	s_lshr_b32 s0, s0, 29
	s_add_i32 s0, s19, s0
	s_and_b32 s1, s0, 0x1fffff8
	s_lshl_b32 s0, s0, 4
	s_and_b32 s12, s0, 0xffffff80
	s_sub_i32 s1, s19, s1
	s_ashr_i32 s13, s12, 31
	s_lshl_b32 s14, s1, 7
	s_lshl_b64 s[0:1], s[12:13], 11
	s_add_u32 s6, s20, s0
	s_addc_u32 s7, s21, s1
	s_ashr_i32 s15, s14, 31
	s_lshl_b64 s[16:17], s[14:15], 11
	s_add_u32 s8, s22, s16
	s_addc_u32 s9, s23, s17
	s_lshl_b64 s[10:11], s[12:13], 4
	s_mov_b32 s13, 0
	s_add_u32 s10, s24, s10
	v_add_u32_e32 v135, s13, v128
	s_waitcnt vmcnt(15)
	v_add_u32_e32 v2, 0x100, v135
	s_waitcnt vmcnt(8)
	v_ashrrev_i32_e32 v40, 3, v135
	v_ashrrev_i32_e32 v42, 3, v2
	s_addc_u32 s11, s25, s11
	v_ashrrev_i32_e32 v41, 31, v40
	v_ashrrev_i32_e32 v43, 31, v42
	v_lshrrev_b32_e32 v218, 1, v135
	v_and_b32_e32 v218, 64, v218
	v_and_b32_e32 v219, 15, v135
	v_or_b32_e32 v218, v218, v219
	v_lshlrev_b32_e32 v218, 4, v218
	global_load_dwordx4 v[24:27], v218, s[10:11]
	global_load_dwordx4 v[28:31], v218, s[10:11] offset:256
	v_add_u32_e32 v2, 0x300, v135
	v_add_u32_e32 v0, 0x200, v135
	s_waitcnt vmcnt(2)
	v_ashrrev_i32_e32 v46, 3, v2
	v_ashrrev_i32_e32 v44, 3, v0
	v_ashrrev_i32_e32 v47, 31, v46
	v_ashrrev_i32_e32 v45, 31, v44
	global_load_dwordx4 v[32:35], v218, s[10:11] offset:768
	global_load_dwordx4 v[36:39], v218, s[10:11] offset:512
	v_lshlrev_b32_e32 v1, 4, v135
	s_mov_b32 s10, 0x358637bd
	v_and_b32_e32 v132, 0x70, v1
	v_mov_b64_e32 v[48:49], s[10:11]
	v_lshl_add_u64 v[58:59], s[6:7], 0, v[132:133]
	s_mov_b32 s6, 0x3b800000
	s_mov_b32 s10, 0x800000
	v_lshl_add_u64 v[60:61], s[8:9], 0, v[132:133]
	v_ashrrev_i32_e32 v0, 1, v135
	v_lshlrev_b64 v[50:51], 11, v[40:41]
	v_lshlrev_b64 v[52:53], 11, v[42:43]
	v_lshlrev_b64 v[54:55], 11, v[44:45]
	v_and_b32_e32 v141, 0xffffffc0, v0
	v_lshl_add_u64 v[0:1], v[58:59], 0, v[50:51]
	v_lshl_add_u64 v[8:9], v[58:59], 0, v[52:53]
	v_lshl_add_u64 v[16:17], v[58:59], 0, v[54:55]
	v_lshl_add_u64 v[2:3], v[60:61], 0, v[50:51]
	v_lshl_add_u64 v[10:11], v[60:61], 0, v[52:53]
	v_lshl_add_u64 v[20:21], v[60:61], 0, v[54:55]
	v_lshlrev_b64 v[56:57], 11, v[46:47]
	v_and_b32_e32 v140, 15, v135
	s_add_u32 s0, s34, s0
	s_addc_u32 s1, s35, s1
	v_bfe_u32 v142, v135, 4, 2
	v_lshl_add_u64 v[112:113], s[0:1], 0, v[50:51]
	v_lshl_add_u64 v[114:115], s[0:1], 0, v[52:53]
	v_lshl_add_u64 v[116:117], s[0:1], 0, v[54:55]
	v_lshl_add_u64 v[118:119], s[0:1], 0, v[56:57]
	s_add_u32 s0, s36, s16
	s_addc_u32 s1, s37, s17
	v_lshl_add_u64 v[120:121], s[0:1], 0, v[50:51]
	v_lshl_add_u64 v[122:123], s[0:1], 0, v[52:53]
	v_lshl_add_u64 v[124:125], s[0:1], 0, v[54:55]
	v_lshl_add_u64 v[126:127], s[0:1], 0, v[56:57]
	v_lshrrev_b32_e32 v218, 3, v135
	v_xor_b32_e32 v218, v218, v135
	v_and_b32_e32 v218, 7, v218
	v_lshlrev_b32_e32 v218, 4, v218
	v_add_u32_e32 v218, 0xffffff80, v218
	v_mov_b32_e32 v219, -1
	v_lshl_add_u64 v[112:113], v[112:113], 0, v[218:219]
	v_lshl_add_u64 v[114:115], v[114:115], 0, v[218:219]
	v_lshl_add_u64 v[116:117], v[116:117], 0, v[218:219]
	v_lshl_add_u64 v[118:119], v[118:119], 0, v[218:219]
	v_lshl_add_u64 v[120:121], v[120:121], 0, v[218:219]
	v_lshl_add_u64 v[122:123], v[122:123], 0, v[218:219]
	v_lshl_add_u64 v[124:125], v[124:125], 0, v[218:219]
	v_lshl_add_u64 v[126:127], v[126:127], 0, v[218:219]
	v_lshrrev_b32_e32 v218, 6, v135
	s_nop 1
	v_readfirstlane_b32 s56, v218
	s_nop 3
	s_lshl_b32 s56, s56, 10
	s_waitcnt lgkmcnt(0)
	s_barrier
	s_mov_b32 m0, s56
	s_nop 0
	global_load_lds_dwordx4 v[112:113], off
	s_add_u32 m0, s56, 0x1000
	s_nop 0
	global_load_lds_dwordx4 v[114:115], off
	s_add_u32 m0, s56, 0x2000
	s_nop 0
	global_load_lds_dwordx4 v[116:117], off
	s_add_u32 m0, s56, 0x3000
	s_nop 0
	global_load_lds_dwordx4 v[118:119], off
	s_add_u32 m0, s56, 0x4000
	s_nop 0
	global_load_lds_dwordx4 v[120:121], off
	s_add_u32 m0, s56, 0x5000
	s_nop 0
	global_load_lds_dwordx4 v[122:123], off
	s_add_u32 m0, s56, 0x6000
	s_nop 0
	global_load_lds_dwordx4 v[124:125], off
	s_add_u32 m0, s56, 0x7000
	s_nop 0
	global_load_lds_dwordx4 v[126:127], off
	v_lshl_add_u64 v[112:113], v[112:113], 0, s[30:31]
	v_lshl_add_u64 v[114:115], v[114:115], 0, s[30:31]
	v_lshl_add_u64 v[116:117], v[116:117], 0, s[30:31]
	v_lshl_add_u64 v[118:119], v[118:119], 0, s[30:31]
	v_lshl_add_u64 v[120:121], v[120:121], 0, s[30:31]
	v_lshl_add_u64 v[122:123], v[122:123], 0, s[30:31]
	v_lshl_add_u64 v[124:125], v[124:125], 0, s[30:31]
	v_lshl_add_u64 v[126:127], v[126:127], 0, s[30:31]
	s_waitcnt vmcnt(11)
	v_mov_b32_e32 v63, v24
	s_waitcnt vmcnt(10)
	v_mov_b32_e32 v62, v28
	v_mov_b32_e32 v24, v29
	v_mov_b32_e32 v28, v30
	v_mov_b32_e32 v29, v26
	v_mov_b32_e32 v26, v31
	v_pk_add_f32 v[24:25], v[62:63], v[24:25]
	s_waitcnt vmcnt(9)
	v_mov_b32_e32 v30, v32
	s_waitcnt vmcnt(8)
; template <int HOOK>
; __device__ __forceinline__ void gemm_tile(const u16* __restrict__ A, int lda, const u16* __restrict__ B, int ldb, int K, char* smem, const float* ssq = nullptr) {
;     ...
;   f32x4 acc[4][4];
; #pragma unroll
;   for (int i = 0; i < 4; i++)
; #pragma unroll
;     for (int j = 0; j < 4; j++) acc[i][j] = (f32x4){0.f, 0.f, 0.f, 0.f};
;   u32x4 ra[4], rb[4];
;   float rs[4];
;   if (HOOK) {
; #pragma unroll
;     for (int i = 0; i < 4; i++) {
;       int row = (tid + i * NTHR) >> 3;
;       float4 q = *(const float4*)(ssq + (size_t)row * 4);
;       rs[i] = rsqrtf((q.x + q.y + q.z + q.w) * (1.f / 256.f) + 1e-6f);
;     }
;   }
; #pragma unroll
;   for (int i = 0; i < 4; i++) {
;     int id = tid + i * NTHR; int row = id >> 3, ch = id & 7;
;     ra[i] = *(const u32x4*)(A + (size_t)row * lda + ch * 8);
;     rb[i] = *(const u32x4*)(B + (size_t)row * ldb + ch * 8);
;   }
; #pragma unroll 1
;   for (int k0 = 0; k0 < K; k0 += 64) {
;     __syncthreads();
;     if (HOOK && k0 >= 512 && k0 < 768) {
; #pragma unroll
;       for (int i = 0; i < 4; i++) {
;         float t8[8];
;         unpack8(ra[i], t8);
; #pragma unroll
;         for (int e = 0; e < 8; e++) t8[e] *= rs[i];
;         ra[i] = pack8(t8);
;       }
;     }
; #pragma unroll
;     for (int i = 0; i < 4; i++) {
;       int id = tid + i * NTHR; int row = id >> 3, ch = id & 7;
;       *(u32x4*)(sA + row * 72 + ch * 8) = ra[i];
;       *(u32x4*)(sB + row * 72 + ch * 8) = rb[i];
;     }
;     __syncthreads();
;     if (k0 + 64 < K) {
; #pragma unroll
;       for (int i = 0; i < 4; i++) {
;         int id = tid + i * NTHR; int row = id >> 3, ch = id & 7;
;         ra[i] = *(const u32x4*)(A + (size_t)row * lda + k0 + 64 + ch * 8);
;         rb[i] = *(const u32x4*)(B + (size_t)row * ldb + k0 + 64 + ch * 8);
;       }
;     }
; #pragma unroll
;     for (int kk = 0; kk < 64; kk += 32) {
;       bf16x8 af[4], bfr[4];
; #pragma unroll
;       for (int i = 0; i < 4; i++) af[i] = *(const bf16x8*)(sA + (wm + i * 16 + lr) * 72 + kk + lq * 8);
; #pragma unroll
;       for (int j = 0; j < 4; j++) bfr[j] = *(const bf16x8*)(sB + (wn + j * 16 + lr) * 72 + kk + lq * 8);
	v_mov_b32_e32 v31, v36
	v_mov_b32_e32 v36, v33
	v_mov_b32_e32 v32, v34
	v_mov_b32_e32 v33, v38
	v_pk_add_f32 v[30:31], v[30:31], v[36:37]
	v_mov_b32_e32 v38, v35
	v_pk_add_f32 v[24:25], v[24:25], v[28:29]
	v_pk_add_f32 v[28:29], v[30:31], v[32:33]
	v_pk_add_f32 v[24:25], v[24:25], v[26:27]
	v_pk_add_f32 v[26:27], v[28:29], v[38:39]
	v_pk_fma_f32 v[24:25], v[24:25], s[6:7], v[48:49] op_sel_hi:[1,0,0]
	v_pk_fma_f32 v[26:27], v[26:27], s[6:7], v[48:49] op_sel_hi:[1,0,0]
	v_mul_f32_e32 v28, 0x4b800000, v25
	v_mul_f32_e32 v29, 0x4b800000, v24
	v_mul_f32_e32 v30, 0x4b800000, v27
	v_mul_f32_e32 v31, 0x4b800000, v26
	v_cmp_gt_f32_e32 vcc, s10, v25
	v_cmp_gt_f32_e64 s[6:7], s10, v24
	v_cmp_gt_f32_e64 s[8:9], s10, v27
	v_cmp_gt_f32_e64 s[10:11], s10, v26
	v_cndmask_b32_e32 v25, v25, v28, vcc
	v_cndmask_b32_e64 v24, v24, v29, s[6:7]
	v_cndmask_b32_e64 v27, v27, v30, s[8:9]
	v_cndmask_b32_e64 v26, v26, v31, s[10:11]
	v_rsq_f32_e32 v25, v25
	v_rsq_f32_e32 v24, v24
	v_rsq_f32_e32 v27, v27
	v_rsq_f32_e32 v26, v26
	v_mul_f32_e32 v28, 0x45800000, v25
	v_mul_f32_e32 v29, 0x45800000, v24
	v_mul_f32_e32 v30, 0x45800000, v27
	v_mul_f32_e32 v31, 0x45800000, v26
	v_cndmask_b32_e32 v96, v25, v28, vcc
	v_cndmask_b32_e64 v98, v24, v29, s[6:7]
	v_cndmask_b32_e64 v100, v27, v30, s[8:9]
	v_cndmask_b32_e64 v102, v26, v31, s[10:11]
	v_lshl_add_u64 v[24:25], v[58:59], 0, v[56:57]
	v_lshl_add_u64 v[26:27], v[60:61], 0, v[56:57]
	v_or_b32_e32 v32, v141, v140
	v_and_b32_e32 v34, 0x4f, v135
	v_mul_lo_u32 v35, v32, s33
	v_and_b32_e32 v32, 7, v135
	v_lshlrev_b32_e32 v33, 4, v142
	v_mad_u64_u32 v[104:105], s[6:7], v40, s33, v[132:133]
	v_mad_u64_u32 v[106:107], s[6:7], v42, s33, v[132:133]
	v_mad_u64_u32 v[108:109], s[6:7], v44, s33, v[132:133]
	v_mad_u64_u32 v[110:111], s[6:7], v46, s33, v[132:133]
	v_mul_u32_u24_e32 v34, 0x90, v34
	v_lshlrev_b32_e32 v132, 4, v32
	v_mov_b32_e32 v32, 0
	v_mov_b32_e32 v103, v102
	v_mov_b32_e32 v101, v100
	v_mov_b32_e32 v99, v98
	v_mov_b32_e32 v97, v96
	s_mov_b32 s6, 0
	v_add_u32_e32 v105, v33, v35
	v_add_u32_e32 v107, v33, v34
	v_mov_b32_e32 v33, v32
	v_mov_b32_e32 v34, v32
	v_mov_b32_e32 v35, v32
	v_mov_b32_e32 v36, v32
	v_mov_b32_e32 v37, v32
	v_mov_b32_e32 v38, v32
	v_mov_b32_e32 v39, v32
	v_mov_b32_e32 v40, v32
	v_mov_b32_e32 v41, v32
	v_mov_b32_e32 v42, v32
	v_mov_b32_e32 v43, v32
	v_mov_b32_e32 v44, v32
	v_mov_b32_e32 v45, v32
	v_mov_b32_e32 v46, v32
	v_mov_b32_e32 v47, v32
	v_mov_b32_e32 v48, v32
	v_mov_b32_e32 v49, v32
	v_mov_b32_e32 v50, v32
	v_mov_b32_e32 v51, v32
	v_mov_b32_e32 v52, v32
	v_mov_b32_e32 v53, v32
	v_mov_b32_e32 v54, v32
	v_mov_b32_e32 v55, v32
	v_mov_b32_e32 v56, v32
	v_mov_b32_e32 v57, v32
	v_mov_b32_e32 v58, v32
	v_mov_b32_e32 v59, v32
	v_mov_b32_e32 v60, v32
	v_mov_b32_e32 v61, v32
	v_mov_b32_e32 v62, v32
	v_mov_b32_e32 v63, v32
	v_mov_b32_e32 v80, v32
	v_mov_b32_e32 v81, v32
	v_mov_b32_e32 v82, v32
	v_mov_b32_e32 v83, v32
	v_mov_b32_e32 v84, v32
	v_mov_b32_e32 v85, v32
	v_mov_b32_e32 v86, v32
	v_mov_b32_e32 v87, v32
	v_mov_b32_e32 v88, v32
	v_mov_b32_e32 v89, v32
	v_mov_b32_e32 v90, v32
	v_mov_b32_e32 v91, v32
	v_mov_b32_e32 v92, v32
	v_mov_b32_e32 v93, v32
	v_mov_b32_e32 v94, v32
	v_mov_b32_e32 v95, v32
	v_mov_b32_e32 v64, v32
	v_mov_b32_e32 v65, v32
	v_mov_b32_e32 v66, v32
	v_mov_b32_e32 v67, v32
	v_mov_b32_e32 v68, v32
	v_mov_b32_e32 v69, v32
	v_mov_b32_e32 v70, v32
	v_mov_b32_e32 v71, v32
	v_mov_b32_e32 v72, v32
	v_mov_b32_e32 v73, v32
	v_mov_b32_e32 v74, v32
	v_mov_b32_e32 v75, v32
	v_mov_b32_e32 v76, v32
	v_mov_b32_e32 v77, v32
	v_mov_b32_e32 v78, v32
	v_mov_b32_e32 v79, v32
	v_and_b32_e32 v209, 7, v140
	v_xor_b32_e32 v209, v209, v142
	v_lshlrev_b32_e32 v209, 4, v209
	v_or_b32_e32 v143, v141, v140
	v_lshl_add_u32 v208, v143, 7, v209
	v_and_b32_e32 v143, 0x4f, v135
	v_lshl_add_u32 v143, v143, 7, v209
	v_xor_b32_e32 v215, 64, v143
	v_xor_b32_e32 v209, 64, v208
	s_waitcnt vmcnt(0)
	s_barrier
.Ldp5_loop:
	ds_read_b128 v[144:147], v208 offset:0
	ds_read_b128 v[148:151], v208 offset:2048
	ds_read_b128 v[152:155], v208 offset:4096
	ds_read_b128 v[156:159], v208 offset:6144
	ds_read_b128 v[160:163], v143 offset:16384
	ds_read_b128 v[164:167], v143 offset:18432
	ds_read_b128 v[168:171], v143 offset:20480
	ds_read_b128 v[172:175], v143 offset:22528
	s_add_u32 m0, s56, 0x8000
	s_nop 0
	global_load_lds_dwordx4 v[112:113], off
	s_add_u32 m0, s56, 0x9000
	s_nop 0
	global_load_lds_dwordx4 v[114:115], off
	s_add_u32 m0, s56, 0xa000
	s_nop 0
	global_load_lds_dwordx4 v[116:117], off
	s_add_u32 m0, s56, 0xb000
	s_nop 0
	global_load_lds_dwordx4 v[118:119], off
	s_add_u32 m0, s56, 0xc000
	s_nop 0
	global_load_lds_dwordx4 v[120:121], off
	s_add_u32 m0, s56, 0xd000
	s_nop 0
	global_load_lds_dwordx4 v[122:123], off
	s_add_u32 m0, s56, 0xe000
	s_nop 0
	global_load_lds_dwordx4 v[124:125], off
	s_add_u32 m0, s56, 0xf000
	s_nop 0
	global_load_lds_dwordx4 v[126:127], off
	s_and_b32 s0, s6, 0x300
	s_cmpk_eq_i32 s0, 0x200
	s_cbranch_scc1 .Ldp5_eh
; DEV f32x4 mfma16(bf16x8 a, bf16x8 b, f32x4 c) { return __builtin_amdgcn_mfma_f32_16x16x32_bf16(a, b, c, 0, 0, 0); }
; template <int HOOK>
; __device__ __forceinline__ void gemm_tile(const u16* __restrict__ A, int lda, const u16* __restrict__ B, int ldb, int K, char* smem, const float* ssq = nullptr) {
;     ...
;     if (HOOK && k0 >= 512 && k0 < 768) {
; #pragma unroll
;       for (int i = 0; i < 4; i++) {
;         float t8[8];
;         unpack8(ra[i], t8);
; #pragma unroll
;         for (int e = 0; e < 8; e++) t8[e] *= rs[i];
;         ra[i] = pack8(t8);
;       }
;     }
; #pragma unroll
;     for (int i = 0; i < 4; i++) {
;       int id = tid + i * NTHR; int row = id >> 3, ch = id & 7;
;       *(u32x4*)(sA + row * 72 + ch * 8) = ra[i];
;       *(u32x4*)(sB + row * 72 + ch * 8) = rb[i];
;     }
;     __syncthreads();
;     if (k0 + 64 < K) {
; #pragma unroll
;       for (int i = 0; i < 4; i++) {
;         int id = tid + i * NTHR; int row = id >> 3, ch = id & 7;
;         ra[i] = *(const u32x4*)(A + (size_t)row * lda + k0 + 64 + ch * 8);
;         rb[i] = *(const u32x4*)(B + (size_t)row * ldb + k0 + 64 + ch * 8);
;       }
;     }
; #pragma unroll
;     for (int kk = 0; kk < 64; kk += 32) {
;       bf16x8 af[4], bfr[4];
; #pragma unroll
;       for (int i = 0; i < 4; i++) af[i] = *(const bf16x8*)(sA + (wm + i * 16 + lr) * 72 + kk + lq * 8);
; #pragma unroll
;       for (int j = 0; j < 4; j++) bfr[j] = *(const bf16x8*)(sB + (wn + j * 16 + lr) * 72 + kk + lq * 8);
;       __builtin_amdgcn_s_setprio(1);
; #pragma unroll
;       for (int i = 0; i < 4; i++)
; #pragma unroll
;         for (int j = 0; j < 4; j++) acc[i][j] = mfma16(af[i], bfr[j], acc[i][j]);
;       __builtin_amdgcn_s_setprio(0);
;     }
	s_setprio 1
	s_waitcnt lgkmcnt(3)
	v_mfma_f32_16x16x32_bf16 v[92:95], v[144:147], v[160:163], v[92:95]
	s_waitcnt lgkmcnt(2)
	v_mfma_f32_16x16x32_bf16 v[88:91], v[144:147], v[164:167], v[88:91]
	s_waitcnt lgkmcnt(1)
	v_mfma_f32_16x16x32_bf16 v[84:87], v[144:147], v[168:171], v[84:87]
	s_waitcnt lgkmcnt(0)
	v_mfma_f32_16x16x32_bf16 v[80:83], v[144:147], v[172:175], v[80:83]
	ds_read_b128 v[176:179], v209 offset:0
	ds_read_b128 v[180:183], v209 offset:2048
	ds_read_b128 v[184:187], v209 offset:4096
	ds_read_b128 v[188:191], v209 offset:6144
	ds_read_b128 v[192:195], v215 offset:16384
	ds_read_b128 v[196:199], v215 offset:18432
	ds_read_b128 v[200:203], v215 offset:20480
	ds_read_b128 v[204:207], v215 offset:22528
	v_mfma_f32_16x16x32_bf16 v[60:63], v[148:151], v[160:163], v[60:63]
	v_lshl_add_u64 v[112:113], v[112:113], 0, s[30:31]
	v_mfma_f32_16x16x32_bf16 v[56:59], v[148:151], v[164:167], v[56:59]
	v_lshl_add_u64 v[114:115], v[114:115], 0, s[30:31]
	v_mfma_f32_16x16x32_bf16 v[52:55], v[148:151], v[168:171], v[52:55]
	v_lshl_add_u64 v[116:117], v[116:117], 0, s[30:31]
	v_mfma_f32_16x16x32_bf16 v[48:51], v[148:151], v[172:175], v[48:51]
	v_lshl_add_u64 v[118:119], v[118:119], 0, s[30:31]
	v_mfma_f32_16x16x32_bf16 v[44:47], v[152:155], v[160:163], v[44:47]
	v_lshl_add_u64 v[120:121], v[120:121], 0, s[30:31]
	v_mfma_f32_16x16x32_bf16 v[40:43], v[152:155], v[164:167], v[40:43]
	v_lshl_add_u64 v[122:123], v[122:123], 0, s[30:31]
	v_mfma_f32_16x16x32_bf16 v[36:39], v[152:155], v[168:171], v[36:39]
	v_lshl_add_u64 v[124:125], v[124:125], 0, s[30:31]
	v_mfma_f32_16x16x32_bf16 v[32:35], v[152:155], v[172:175], v[32:35]
	v_lshl_add_u64 v[126:127], v[126:127], 0, s[30:31]
	v_mfma_f32_16x16x32_bf16 v[64:67], v[156:159], v[160:163], v[64:67]
	v_mfma_f32_16x16x32_bf16 v[68:71], v[156:159], v[164:167], v[68:71]
	v_mfma_f32_16x16x32_bf16 v[72:75], v[156:159], v[168:171], v[72:75]
	v_mfma_f32_16x16x32_bf16 v[76:79], v[156:159], v[172:175], v[76:79]
	s_waitcnt lgkmcnt(3)
	v_mfma_f32_16x16x32_bf16 v[92:95], v[176:179], v[192:195], v[92:95]
	s_waitcnt lgkmcnt(2)
	v_mfma_f32_16x16x32_bf16 v[88:91], v[176:179], v[196:199], v[88:91]
	s_waitcnt lgkmcnt(1)
	v_mfma_f32_16x16x32_bf16 v[84:87], v[176:179], v[200:203], v[84:87]
	s_waitcnt lgkmcnt(0)
	v_mfma_f32_16x16x32_bf16 v[80:83], v[176:179], v[204:207], v[80:83]
	v_mfma_f32_16x16x32_bf16 v[60:63], v[180:183], v[192:195], v[60:63]
	v_mfma_f32_16x16x32_bf16 v[56:59], v[180:183], v[196:199], v[56:59]
	v_mfma_f32_16x16x32_bf16 v[52:55], v[180:183], v[200:203], v[52:55]
	v_mfma_f32_16x16x32_bf16 v[48:51], v[180:183], v[204:207], v[48:51]
	v_mfma_f32_16x16x32_bf16 v[44:47], v[184:187], v[192:195], v[44:47]
	v_mfma_f32_16x16x32_bf16 v[40:43], v[184:187], v[196:199], v[40:43]
	v_mfma_f32_16x16x32_bf16 v[36:39], v[184:187], v[200:203], v[36:39]
	v_mfma_f32_16x16x32_bf16 v[32:35], v[184:187], v[204:207], v[32:35]
	v_mfma_f32_16x16x32_bf16 v[64:67], v[188:191], v[192:195], v[64:67]
	v_mfma_f32_16x16x32_bf16 v[68:71], v[188:191], v[196:199], v[68:71]
	v_mfma_f32_16x16x32_bf16 v[72:75], v[188:191], v[200:203], v[72:75]
	v_mfma_f32_16x16x32_bf16 v[76:79], v[188:191], v[204:207], v[76:79]
	s_setprio 0
	s_branch .Ldp5_ee
.Ldp5_eh:
	s_waitcnt lgkmcnt(0)
	ds_read_b128 v[176:179], v209 offset:0
	ds_read_b128 v[180:183], v209 offset:2048
	ds_read_b128 v[184:187], v209 offset:4096
	ds_read_b128 v[188:191], v209 offset:6144
	ds_read_b128 v[192:195], v215 offset:16384
	ds_read_b128 v[196:199], v215 offset:18432
	ds_read_b128 v[200:203], v215 offset:20480
	ds_read_b128 v[204:207], v215 offset:22528
	v_lshlrev_b32_e32 v0, 16, v144
	v_and_b32_e32 v1, 0xffff0000, v144
	v_pk_mul_f32 v[0:1], v[96:97], v[0:1]
	v_cvt_pk_bf16_f32 v144, v0, v1
	v_lshlrev_b32_e32 v2, 16, v145
	v_and_b32_e32 v3, 0xffff0000, v145
	v_pk_mul_f32 v[2:3], v[96:97], v[2:3]
	v_cvt_pk_bf16_f32 v145, v2, v3
	v_lshlrev_b32_e32 v4, 16, v146
	v_and_b32_e32 v5, 0xffff0000, v146
	v_pk_mul_f32 v[4:5], v[96:97], v[4:5]
	v_cvt_pk_bf16_f32 v146, v4, v5
	v_lshlrev_b32_e32 v6, 16, v147
	v_and_b32_e32 v7, 0xffff0000, v147
	v_pk_mul_f32 v[6:7], v[96:97], v[6:7]
	v_cvt_pk_bf16_f32 v147, v6, v7
	v_lshlrev_b32_e32 v8, 16, v148
	v_and_b32_e32 v9, 0xffff0000, v148
	v_pk_mul_f32 v[8:9], v[98:99], v[8:9]
	v_cvt_pk_bf16_f32 v148, v8, v9
	v_lshlrev_b32_e32 v10, 16, v149
	v_and_b32_e32 v11, 0xffff0000, v149
	v_pk_mul_f32 v[10:11], v[98:99], v[10:11]
	v_cvt_pk_bf16_f32 v149, v10, v11
	v_lshlrev_b32_e32 v12, 16, v150
	v_and_b32_e32 v13, 0xffff0000, v150
	v_pk_mul_f32 v[12:13], v[98:99], v[12:13]
	v_cvt_pk_bf16_f32 v150, v12, v13
	v_lshlrev_b32_e32 v14, 16, v151
	v_and_b32_e32 v15, 0xffff0000, v151
	v_pk_mul_f32 v[14:15], v[98:99], v[14:15]
	v_cvt_pk_bf16_f32 v151, v14, v15
	v_lshlrev_b32_e32 v0, 16, v152
	v_and_b32_e32 v1, 0xffff0000, v152
	v_pk_mul_f32 v[0:1], v[100:101], v[0:1]
	v_cvt_pk_bf16_f32 v152, v0, v1
	v_lshlrev_b32_e32 v2, 16, v153
	v_and_b32_e32 v3, 0xffff0000, v153
	v_pk_mul_f32 v[2:3], v[100:101], v[2:3]
	v_cvt_pk_bf16_f32 v153, v2, v3
	v_lshlrev_b32_e32 v4, 16, v154
	v_and_b32_e32 v5, 0xffff0000, v154
	v_pk_mul_f32 v[4:5], v[100:101], v[4:5]
	v_cvt_pk_bf16_f32 v154, v4, v5
	v_lshlrev_b32_e32 v6, 16, v155
	v_and_b32_e32 v7, 0xffff0000, v155
	v_pk_mul_f32 v[6:7], v[100:101], v[6:7]
	v_cvt_pk_bf16_f32 v155, v6, v7
	v_lshlrev_b32_e32 v8, 16, v156
	v_and_b32_e32 v9, 0xffff0000, v156
	v_pk_mul_f32 v[8:9], v[102:103], v[8:9]
	v_cvt_pk_bf16_f32 v156, v8, v9
	v_lshlrev_b32_e32 v10, 16, v157
	v_and_b32_e32 v11, 0xffff0000, v157
	v_pk_mul_f32 v[10:11], v[102:103], v[10:11]
	v_cvt_pk_bf16_f32 v157, v10, v11
	v_lshlrev_b32_e32 v12, 16, v158
	v_and_b32_e32 v13, 0xffff0000, v158
; DEV f32x4 mfma16(bf16x8 a, bf16x8 b, f32x4 c) { return __builtin_amdgcn_mfma_f32_16x16x32_bf16(a, b, c, 0, 0, 0); }
; template <int HOOK>
; __device__ __forceinline__ void gemm_tile(const u16* __restrict__ A, int lda, const u16* __restrict__ B, int ldb, int K, char* smem, const float* ssq = nullptr) {
;     ...
;     if (HOOK && k0 >= 512 && k0 < 768) {
; #pragma unroll
;       for (int i = 0; i < 4; i++) {
;         float t8[8];
;         unpack8(ra[i], t8);
; #pragma unroll
;         for (int e = 0; e < 8; e++) t8[e] *= rs[i];
;         ra[i] = pack8(t8);
;       }
;     }
; #pragma unroll
;     for (int i = 0; i < 4; i++) {
;       int id = tid + i * NTHR; int row = id >> 3, ch = id & 7;
;       *(u32x4*)(sA + row * 72 + ch * 8) = ra[i];
;       *(u32x4*)(sB + row * 72 + ch * 8) = rb[i];
;     }
;     __syncthreads();
;     if (k0 + 64 < K) {
; #pragma unroll
;       for (int i = 0; i < 4; i++) {
;         int id = tid + i * NTHR; int row = id >> 3, ch = id & 7;
;         ra[i] = *(const u32x4*)(A + (size_t)row * lda + k0 + 64 + ch * 8);
;         rb[i] = *(const u32x4*)(B + (size_t)row * ldb + k0 + 64 + ch * 8);
;       }
;     }
; #pragma unroll
;     for (int kk = 0; kk < 64; kk += 32) {
;       bf16x8 af[4], bfr[4];
; #pragma unroll
;       for (int i = 0; i < 4; i++) af[i] = *(const bf16x8*)(sA + (wm + i * 16 + lr) * 72 + kk + lq * 8);
; #pragma unroll
;       for (int j = 0; j < 4; j++) bfr[j] = *(const bf16x8*)(sB + (wn + j * 16 + lr) * 72 + kk + lq * 8);
;       __builtin_amdgcn_s_setprio(1);
; #pragma unroll
;       for (int i = 0; i < 4; i++)
; #pragma unroll
;         for (int j = 0; j < 4; j++) acc[i][j] = mfma16(af[i], bfr[j], acc[i][j]);
;       __builtin_amdgcn_s_setprio(0);
;     }
	v_pk_mul_f32 v[12:13], v[102:103], v[12:13]
	v_cvt_pk_bf16_f32 v158, v12, v13
	v_lshlrev_b32_e32 v14, 16, v159
	v_and_b32_e32 v15, 0xffff0000, v159
	v_pk_mul_f32 v[14:15], v[102:103], v[14:15]
	v_cvt_pk_bf16_f32 v159, v14, v15
	s_nop 1
	s_setprio 1
	v_mfma_f32_16x16x32_bf16 v[92:95], v[144:147], v[160:163], v[92:95]
	v_mfma_f32_16x16x32_bf16 v[88:91], v[144:147], v[164:167], v[88:91]
	v_mfma_f32_16x16x32_bf16 v[84:87], v[144:147], v[168:171], v[84:87]
	v_mfma_f32_16x16x32_bf16 v[80:83], v[144:147], v[172:175], v[80:83]
	v_mfma_f32_16x16x32_bf16 v[60:63], v[148:151], v[160:163], v[60:63]
	v_lshl_add_u64 v[112:113], v[112:113], 0, s[30:31]
	v_mfma_f32_16x16x32_bf16 v[56:59], v[148:151], v[164:167], v[56:59]
	v_lshl_add_u64 v[114:115], v[114:115], 0, s[30:31]
	v_mfma_f32_16x16x32_bf16 v[52:55], v[148:151], v[168:171], v[52:55]
	v_lshl_add_u64 v[116:117], v[116:117], 0, s[30:31]
	v_mfma_f32_16x16x32_bf16 v[48:51], v[148:151], v[172:175], v[48:51]
	v_lshl_add_u64 v[118:119], v[118:119], 0, s[30:31]
	v_mfma_f32_16x16x32_bf16 v[44:47], v[152:155], v[160:163], v[44:47]
	v_lshl_add_u64 v[120:121], v[120:121], 0, s[30:31]
	v_mfma_f32_16x16x32_bf16 v[40:43], v[152:155], v[164:167], v[40:43]
	v_lshl_add_u64 v[122:123], v[122:123], 0, s[30:31]
	v_mfma_f32_16x16x32_bf16 v[36:39], v[152:155], v[168:171], v[36:39]
	v_lshl_add_u64 v[124:125], v[124:125], 0, s[30:31]
	v_mfma_f32_16x16x32_bf16 v[32:35], v[152:155], v[172:175], v[32:35]
	v_lshl_add_u64 v[126:127], v[126:127], 0, s[30:31]
	v_mfma_f32_16x16x32_bf16 v[64:67], v[156:159], v[160:163], v[64:67]
	v_mfma_f32_16x16x32_bf16 v[68:71], v[156:159], v[164:167], v[68:71]
	v_mfma_f32_16x16x32_bf16 v[72:75], v[156:159], v[168:171], v[72:75]
	v_mfma_f32_16x16x32_bf16 v[76:79], v[156:159], v[172:175], v[76:79]
	s_setprio 0
	s_waitcnt lgkmcnt(0)
	v_lshlrev_b32_e32 v0, 16, v176
	v_and_b32_e32 v1, 0xffff0000, v176
	v_pk_mul_f32 v[0:1], v[96:97], v[0:1]
	v_cvt_pk_bf16_f32 v176, v0, v1
	v_lshlrev_b32_e32 v2, 16, v177
	v_and_b32_e32 v3, 0xffff0000, v177
	v_pk_mul_f32 v[2:3], v[96:97], v[2:3]
	v_cvt_pk_bf16_f32 v177, v2, v3
	v_lshlrev_b32_e32 v4, 16, v178
	v_and_b32_e32 v5, 0xffff0000, v178
	v_pk_mul_f32 v[4:5], v[96:97], v[4:5]
	v_cvt_pk_bf16_f32 v178, v4, v5
	v_lshlrev_b32_e32 v6, 16, v179
	v_and_b32_e32 v7, 0xffff0000, v179
	v_pk_mul_f32 v[6:7], v[96:97], v[6:7]
	v_cvt_pk_bf16_f32 v179, v6, v7
	v_lshlrev_b32_e32 v8, 16, v180
	v_and_b32_e32 v9, 0xffff0000, v180
	v_pk_mul_f32 v[8:9], v[98:99], v[8:9]
	v_cvt_pk_bf16_f32 v180, v8, v9
	v_lshlrev_b32_e32 v10, 16, v181
	v_and_b32_e32 v11, 0xffff0000, v181
	v_pk_mul_f32 v[10:11], v[98:99], v[10:11]
	v_cvt_pk_bf16_f32 v181, v10, v11
	v_lshlrev_b32_e32 v12, 16, v182
	v_and_b32_e32 v13, 0xffff0000, v182
	v_pk_mul_f32 v[12:13], v[98:99], v[12:13]
	v_cvt_pk_bf16_f32 v182, v12, v13
	v_lshlrev_b32_e32 v14, 16, v183
	v_and_b32_e32 v15, 0xffff0000, v183
	v_pk_mul_f32 v[14:15], v[98:99], v[14:15]
	v_cvt_pk_bf16_f32 v183, v14, v15
	v_lshlrev_b32_e32 v0, 16, v184
	v_and_b32_e32 v1, 0xffff0000, v184
	v_pk_mul_f32 v[0:1], v[100:101], v[0:1]
	v_cvt_pk_bf16_f32 v184, v0, v1
	v_lshlrev_b32_e32 v2, 16, v185
	v_and_b32_e32 v3, 0xffff0000, v185
	v_pk_mul_f32 v[2:3], v[100:101], v[2:3]
	v_cvt_pk_bf16_f32 v185, v2, v3
	v_lshlrev_b32_e32 v4, 16, v186
	v_and_b32_e32 v5, 0xffff0000, v186
	v_pk_mul_f32 v[4:5], v[100:101], v[4:5]
	v_cvt_pk_bf16_f32 v186, v4, v5
	v_lshlrev_b32_e32 v6, 16, v187
	v_and_b32_e32 v7, 0xffff0000, v187
	v_pk_mul_f32 v[6:7], v[100:101], v[6:7]
	v_cvt_pk_bf16_f32 v187, v6, v7
	v_lshlrev_b32_e32 v8, 16, v188
	v_and_b32_e32 v9, 0xffff0000, v188
	v_pk_mul_f32 v[8:9], v[102:103], v[8:9]
	v_cvt_pk_bf16_f32 v188, v8, v9
	v_lshlrev_b32_e32 v10, 16, v189
	v_and_b32_e32 v11, 0xffff0000, v189
	v_pk_mul_f32 v[10:11], v[102:103], v[10:11]
	v_cvt_pk_bf16_f32 v189, v10, v11
	v_lshlrev_b32_e32 v12, 16, v190
	v_and_b32_e32 v13, 0xffff0000, v190
	v_pk_mul_f32 v[12:13], v[102:103], v[12:13]
	v_cvt_pk_bf16_f32 v190, v12, v13
	v_lshlrev_b32_e32 v14, 16, v191
	v_and_b32_e32 v15, 0xffff0000, v191
	v_pk_mul_f32 v[14:15], v[102:103], v[14:15]
	v_cvt_pk_bf16_f32 v191, v14, v15
	s_nop 1
	s_setprio 1
	v_mfma_f32_16x16x32_bf16 v[92:95], v[176:179], v[192:195], v[92:95]
	v_mfma_f32_16x16x32_bf16 v[88:91], v[176:179], v[196:199], v[88:91]
	v_mfma_f32_16x16x32_bf16 v[84:87], v[176:179], v[200:203], v[84:87]
	v_mfma_f32_16x16x32_bf16 v[80:83], v[176:179], v[204:207], v[80:83]
	v_mfma_f32_16x16x32_bf16 v[60:63], v[180:183], v[192:195], v[60:63]
	v_mfma_f32_16x16x32_bf16 v[56:59], v[180:183], v[196:199], v[56:59]
	v_mfma_f32_16x16x32_bf16 v[52:55], v[180:183], v[200:203], v[52:55]
	v_mfma_f32_16x16x32_bf16 v[48:51], v[180:183], v[204:207], v[48:51]
	v_mfma_f32_16x16x32_bf16 v[44:47], v[184:187], v[192:195], v[44:47]
	v_mfma_f32_16x16x32_bf16 v[40:43], v[184:187], v[196:199], v[40:43]
	v_mfma_f32_16x16x32_bf16 v[36:39], v[184:187], v[200:203], v[36:39]
	v_mfma_f32_16x16x32_bf16 v[32:35], v[184:187], v[204:207], v[32:35]
	v_mfma_f32_16x16x32_bf16 v[64:67], v[188:191], v[192:195], v[64:67]
	v_mfma_f32_16x16x32_bf16 v[68:71], v[188:191], v[196:199], v[68:71]
	v_mfma_f32_16x16x32_bf16 v[72:75], v[188:191], v[200:203], v[72:75]
	v_mfma_f32_16x16x32_bf16 v[76:79], v[188:191], v[204:207], v[76:79]
	s_setprio 0
; DEV f32x4 mfma16(bf16x8 a, bf16x8 b, f32x4 c) { return __builtin_amdgcn_mfma_f32_16x16x32_bf16(a, b, c, 0, 0, 0); }
; template <int HOOK>
; __device__ __forceinline__ void gemm_tile(const u16* __restrict__ A, int lda, const u16* __restrict__ B, int ldb, int K, char* smem, const float* ssq = nullptr) {
;     ...
;   for (int k0 = 0; k0 < K; k0 += 64) {
;     __syncthreads();
;     if (HOOK && k0 >= 512 && k0 < 768) {
; #pragma unroll
;       for (int i = 0; i < 4; i++) {
;         float t8[8];
;         unpack8(ra[i], t8);
; #pragma unroll
;         for (int e = 0; e < 8; e++) t8[e] *= rs[i];
;         ra[i] = pack8(t8);
;       }
;     }
; #pragma unroll
;     for (int i = 0; i < 4; i++) {
;       int id = tid + i * NTHR; int row = id >> 3, ch = id & 7;
;       *(u32x4*)(sA + row * 72 + ch * 8) = ra[i];
;       *(u32x4*)(sB + row * 72 + ch * 8) = rb[i];
;     }
;     __syncthreads();
;     if (k0 + 64 < K) {
; #pragma unroll
;       for (int i = 0; i < 4; i++) {
;         int id = tid + i * NTHR; int row = id >> 3, ch = id & 7;
;         ra[i] = *(const u32x4*)(A + (size_t)row * lda + k0 + 64 + ch * 8);
;         rb[i] = *(const u32x4*)(B + (size_t)row * ldb + k0 + 64 + ch * 8);
;       }
;     }
; #pragma unroll
;     for (int kk = 0; kk < 64; kk += 32) {
;       bf16x8 af[4], bfr[4];
; #pragma unroll
;       for (int i = 0; i < 4; i++) af[i] = *(const bf16x8*)(sA + (wm + i * 16 + lr) * 72 + kk + lq * 8);
; #pragma unroll
;       for (int j = 0; j < 4; j++) bfr[j] = *(const bf16x8*)(sB + (wn + j * 16 + lr) * 72 + kk + lq * 8);
;       __builtin_amdgcn_s_setprio(1);
; #pragma unroll
;       for (int i = 0; i < 4; i++)
; #pragma unroll
;         for (int j = 0; j < 4; j++) acc[i][j] = mfma16(af[i], bfr[j], acc[i][j]);
;       __builtin_amdgcn_s_setprio(0);
;     }
.Ldp5_ee:
	s_waitcnt vmcnt(0)
	s_barrier
	s_add_i32 s6, s6, 0x80
	ds_read_b128 v[144:147], v208 offset:32768
	ds_read_b128 v[148:151], v208 offset:34816
	ds_read_b128 v[152:155], v208 offset:36864
	ds_read_b128 v[156:159], v208 offset:38912
	ds_read_b128 v[160:163], v143 offset:49152
	ds_read_b128 v[164:167], v143 offset:51200
	ds_read_b128 v[168:171], v143 offset:53248
	ds_read_b128 v[172:175], v143 offset:55296
	s_cmpk_lt_u32 s6, 0x400
	s_cbranch_scc0 .Ldp5_nodma
	s_mov_b32 m0, s56
	s_nop 0
	global_load_lds_dwordx4 v[112:113], off
	s_add_u32 m0, s56, 0x1000
	s_nop 0
	global_load_lds_dwordx4 v[114:115], off
	s_add_u32 m0, s56, 0x2000
	s_nop 0
	global_load_lds_dwordx4 v[116:117], off
	s_add_u32 m0, s56, 0x3000
	s_nop 0
	global_load_lds_dwordx4 v[118:119], off
	s_add_u32 m0, s56, 0x4000
	s_nop 0
	global_load_lds_dwordx4 v[120:121], off
	s_add_u32 m0, s56, 0x5000
	s_nop 0
	global_load_lds_dwordx4 v[122:123], off
	s_add_u32 m0, s56, 0x6000
	s_nop 0
	global_load_lds_dwordx4 v[124:125], off
	s_add_u32 m0, s56, 0x7000
	s_nop 0
	global_load_lds_dwordx4 v[126:127], off
.Ldp5_nodma:
	s_sub_i32 s0, s6, 64
	s_and_b32 s0, s0, 0x300
	s_cmpk_eq_i32 s0, 0x200
	s_cbranch_scc1 .Ldp5_oh
	s_setprio 1
	s_waitcnt lgkmcnt(3)
	v_mfma_f32_16x16x32_bf16 v[92:95], v[144:147], v[160:163], v[92:95]
	s_waitcnt lgkmcnt(2)
	v_mfma_f32_16x16x32_bf16 v[88:91], v[144:147], v[164:167], v[88:91]
	s_waitcnt lgkmcnt(1)
	v_mfma_f32_16x16x32_bf16 v[84:87], v[144:147], v[168:171], v[84:87]
	s_waitcnt lgkmcnt(0)
	v_mfma_f32_16x16x32_bf16 v[80:83], v[144:147], v[172:175], v[80:83]
	ds_read_b128 v[176:179], v209 offset:32768
	ds_read_b128 v[180:183], v209 offset:34816
	ds_read_b128 v[184:187], v209 offset:36864
	ds_read_b128 v[188:191], v209 offset:38912
	ds_read_b128 v[192:195], v215 offset:49152
	ds_read_b128 v[196:199], v215 offset:51200
	ds_read_b128 v[200:203], v215 offset:53248
	ds_read_b128 v[204:207], v215 offset:55296
	v_mfma_f32_16x16x32_bf16 v[60:63], v[148:151], v[160:163], v[60:63]
	v_lshl_add_u64 v[112:113], v[112:113], 0, s[30:31]
	v_mfma_f32_16x16x32_bf16 v[56:59], v[148:151], v[164:167], v[56:59]
	v_lshl_add_u64 v[114:115], v[114:115], 0, s[30:31]
	v_mfma_f32_16x16x32_bf16 v[52:55], v[148:151], v[168:171], v[52:55]
	v_lshl_add_u64 v[116:117], v[116:117], 0, s[30:31]
	v_mfma_f32_16x16x32_bf16 v[48:51], v[148:151], v[172:175], v[48:51]
	v_lshl_add_u64 v[118:119], v[118:119], 0, s[30:31]
	v_mfma_f32_16x16x32_bf16 v[44:47], v[152:155], v[160:163], v[44:47]
	v_lshl_add_u64 v[120:121], v[120:121], 0, s[30:31]
	v_mfma_f32_16x16x32_bf16 v[40:43], v[152:155], v[164:167], v[40:43]
	v_lshl_add_u64 v[122:123], v[122:123], 0, s[30:31]
	v_mfma_f32_16x16x32_bf16 v[36:39], v[152:155], v[168:171], v[36:39]
	v_lshl_add_u64 v[124:125], v[124:125], 0, s[30:31]
	v_mfma_f32_16x16x32_bf16 v[32:35], v[152:155], v[172:175], v[32:35]
	v_lshl_add_u64 v[126:127], v[126:127], 0, s[30:31]
	v_mfma_f32_16x16x32_bf16 v[64:67], v[156:159], v[160:163], v[64:67]
	v_mfma_f32_16x16x32_bf16 v[68:71], v[156:159], v[164:167], v[68:71]
	v_mfma_f32_16x16x32_bf16 v[72:75], v[156:159], v[168:171], v[72:75]
	v_mfma_f32_16x16x32_bf16 v[76:79], v[156:159], v[172:175], v[76:79]
	s_waitcnt lgkmcnt(3)
	v_mfma_f32_16x16x32_bf16 v[92:95], v[176:179], v[192:195], v[92:95]
	s_waitcnt lgkmcnt(2)
	v_mfma_f32_16x16x32_bf16 v[88:91], v[176:179], v[196:199], v[88:91]
	s_waitcnt lgkmcnt(1)
	v_mfma_f32_16x16x32_bf16 v[84:87], v[176:179], v[200:203], v[84:87]
	s_waitcnt lgkmcnt(0)
	v_mfma_f32_16x16x32_bf16 v[80:83], v[176:179], v[204:207], v[80:83]
	v_mfma_f32_16x16x32_bf16 v[60:63], v[180:183], v[192:195], v[60:63]
	v_mfma_f32_16x16x32_bf16 v[56:59], v[180:183], v[196:199], v[56:59]
	v_mfma_f32_16x16x32_bf16 v[52:55], v[180:183], v[200:203], v[52:55]
	v_mfma_f32_16x16x32_bf16 v[48:51], v[180:183], v[204:207], v[48:51]
	v_mfma_f32_16x16x32_bf16 v[44:47], v[184:187], v[192:195], v[44:47]
	v_mfma_f32_16x16x32_bf16 v[40:43], v[184:187], v[196:199], v[40:43]
	v_mfma_f32_16x16x32_bf16 v[36:39], v[184:187], v[200:203], v[36:39]
	v_mfma_f32_16x16x32_bf16 v[32:35], v[184:187], v[204:207], v[32:35]
	v_mfma_f32_16x16x32_bf16 v[64:67], v[188:191], v[192:195], v[64:67]
	v_mfma_f32_16x16x32_bf16 v[68:71], v[188:191], v[196:199], v[68:71]
	v_mfma_f32_16x16x32_bf16 v[72:75], v[188:191], v[200:203], v[72:75]
	v_mfma_f32_16x16x32_bf16 v[76:79], v[188:191], v[204:207], v[76:79]
	s_setprio 0
	s_branch .Ldp5_oe
; DEV f32x4 mfma16(bf16x8 a, bf16x8 b, f32x4 c) { return __builtin_amdgcn_mfma_f32_16x16x32_bf16(a, b, c, 0, 0, 0); }
; template <int HOOK>
; __device__ __forceinline__ void gemm_tile(const u16* __restrict__ A, int lda, const u16* __restrict__ B, int ldb, int K, char* smem, const float* ssq = nullptr) {
;     ...
;     if (HOOK && k0 >= 512 && k0 < 768) {
; #pragma unroll
;       for (int i = 0; i < 4; i++) {
;         float t8[8];
;         unpack8(ra[i], t8);
; #pragma unroll
;         for (int e = 0; e < 8; e++) t8[e] *= rs[i];
;         ra[i] = pack8(t8);
;       }
;     }
; #pragma unroll
;     for (int i = 0; i < 4; i++) {
;       int id = tid + i * NTHR; int row = id >> 3, ch = id & 7;
;       *(u32x4*)(sA + row * 72 + ch * 8) = ra[i];
;       *(u32x4*)(sB + row * 72 + ch * 8) = rb[i];
;     }
;     __syncthreads();
;     if (k0 + 64 < K) {
; #pragma unroll
;       for (int i = 0; i < 4; i++) {
;         int id = tid + i * NTHR; int row = id >> 3, ch = id & 7;
;         ra[i] = *(const u32x4*)(A + (size_t)row * lda + k0 + 64 + ch * 8);
;         rb[i] = *(const u32x4*)(B + (size_t)row * ldb + k0 + 64 + ch * 8);
;       }
;     }
; #pragma unroll
;     for (int kk = 0; kk < 64; kk += 32) {
;       bf16x8 af[4], bfr[4];
; #pragma unroll
;       for (int i = 0; i < 4; i++) af[i] = *(const bf16x8*)(sA + (wm + i * 16 + lr) * 72 + kk + lq * 8);
; #pragma unroll
;       for (int j = 0; j < 4; j++) bfr[j] = *(const bf16x8*)(sB + (wn + j * 16 + lr) * 72 + kk + lq * 8);
;       __builtin_amdgcn_s_setprio(1);
; #pragma unroll
;       for (int i = 0; i < 4; i++)
; #pragma unroll
;         for (int j = 0; j < 4; j++) acc[i][j] = mfma16(af[i], bfr[j], acc[i][j]);
;       __builtin_amdgcn_s_setprio(0);
;     }
.Ldp5_oh:
	s_waitcnt lgkmcnt(0)
	ds_read_b128 v[176:179], v209 offset:32768
	ds_read_b128 v[180:183], v209 offset:34816
	ds_read_b128 v[184:187], v209 offset:36864
	ds_read_b128 v[188:191], v209 offset:38912
	ds_read_b128 v[192:195], v215 offset:49152
	ds_read_b128 v[196:199], v215 offset:51200
	ds_read_b128 v[200:203], v215 offset:53248
	ds_read_b128 v[204:207], v215 offset:55296
	v_lshlrev_b32_e32 v0, 16, v144
	v_and_b32_e32 v1, 0xffff0000, v144
	v_pk_mul_f32 v[0:1], v[96:97], v[0:1]
	v_cvt_pk_bf16_f32 v144, v0, v1
	v_lshlrev_b32_e32 v2, 16, v145
	v_and_b32_e32 v3, 0xffff0000, v145
	v_pk_mul_f32 v[2:3], v[96:97], v[2:3]
	v_cvt_pk_bf16_f32 v145, v2, v3
	v_lshlrev_b32_e32 v4, 16, v146
	v_and_b32_e32 v5, 0xffff0000, v146
	v_pk_mul_f32 v[4:5], v[96:97], v[4:5]
	v_cvt_pk_bf16_f32 v146, v4, v5
	v_lshlrev_b32_e32 v6, 16, v147
	v_and_b32_e32 v7, 0xffff0000, v147
	v_pk_mul_f32 v[6:7], v[96:97], v[6:7]
	v_cvt_pk_bf16_f32 v147, v6, v7
	v_lshlrev_b32_e32 v8, 16, v148
	v_and_b32_e32 v9, 0xffff0000, v148
	v_pk_mul_f32 v[8:9], v[98:99], v[8:9]
	v_cvt_pk_bf16_f32 v148, v8, v9
	v_lshlrev_b32_e32 v10, 16, v149
	v_and_b32_e32 v11, 0xffff0000, v149
	v_pk_mul_f32 v[10:11], v[98:99], v[10:11]
	v_cvt_pk_bf16_f32 v149, v10, v11
	v_lshlrev_b32_e32 v12, 16, v150
	v_and_b32_e32 v13, 0xffff0000, v150
	v_pk_mul_f32 v[12:13], v[98:99], v[12:13]
	v_cvt_pk_bf16_f32 v150, v12, v13
	v_lshlrev_b32_e32 v14, 16, v151
	v_and_b32_e32 v15, 0xffff0000, v151
	v_pk_mul_f32 v[14:15], v[98:99], v[14:15]
	v_cvt_pk_bf16_f32 v151, v14, v15
	v_lshlrev_b32_e32 v0, 16, v152
	v_and_b32_e32 v1, 0xffff0000, v152
	v_pk_mul_f32 v[0:1], v[100:101], v[0:1]
	v_cvt_pk_bf16_f32 v152, v0, v1
	v_lshlrev_b32_e32 v2, 16, v153
	v_and_b32_e32 v3, 0xffff0000, v153
	v_pk_mul_f32 v[2:3], v[100:101], v[2:3]
	v_cvt_pk_bf16_f32 v153, v2, v3
	v_lshlrev_b32_e32 v4, 16, v154
	v_and_b32_e32 v5, 0xffff0000, v154
	v_pk_mul_f32 v[4:5], v[100:101], v[4:5]
	v_cvt_pk_bf16_f32 v154, v4, v5
	v_lshlrev_b32_e32 v6, 16, v155
	v_and_b32_e32 v7, 0xffff0000, v155
	v_pk_mul_f32 v[6:7], v[100:101], v[6:7]
	v_cvt_pk_bf16_f32 v155, v6, v7
	v_lshlrev_b32_e32 v8, 16, v156
	v_and_b32_e32 v9, 0xffff0000, v156
	v_pk_mul_f32 v[8:9], v[102:103], v[8:9]
	v_cvt_pk_bf16_f32 v156, v8, v9
	v_lshlrev_b32_e32 v10, 16, v157
	v_and_b32_e32 v11, 0xffff0000, v157
	v_pk_mul_f32 v[10:11], v[102:103], v[10:11]
	v_cvt_pk_bf16_f32 v157, v10, v11
	v_lshlrev_b32_e32 v12, 16, v158
	v_and_b32_e32 v13, 0xffff0000, v158
	v_pk_mul_f32 v[12:13], v[102:103], v[12:13]
	v_cvt_pk_bf16_f32 v158, v12, v13
	v_lshlrev_b32_e32 v14, 16, v159
	v_and_b32_e32 v15, 0xffff0000, v159
	v_pk_mul_f32 v[14:15], v[102:103], v[14:15]
	v_cvt_pk_bf16_f32 v159, v14, v15
	s_nop 1
	s_setprio 1
	v_mfma_f32_16x16x32_bf16 v[92:95], v[144:147], v[160:163], v[92:95]
	v_mfma_f32_16x16x32_bf16 v[88:91], v[144:147], v[164:167], v[88:91]
	v_mfma_f32_16x16x32_bf16 v[84:87], v[144:147], v[168:171], v[84:87]
	v_mfma_f32_16x16x32_bf16 v[80:83], v[144:147], v[172:175], v[80:83]
	v_mfma_f32_16x16x32_bf16 v[60:63], v[148:151], v[160:163], v[60:63]
	v_lshl_add_u64 v[112:113], v[112:113], 0, s[30:31]
	v_mfma_f32_16x16x32_bf16 v[56:59], v[148:151], v[164:167], v[56:59]
	v_lshl_add_u64 v[114:115], v[114:115], 0, s[30:31]
	v_mfma_f32_16x16x32_bf16 v[52:55], v[148:151], v[168:171], v[52:55]
	v_lshl_add_u64 v[116:117], v[116:117], 0, s[30:31]
	v_mfma_f32_16x16x32_bf16 v[48:51], v[148:151], v[172:175], v[48:51]
	v_lshl_add_u64 v[118:119], v[118:119], 0, s[30:31]
	v_mfma_f32_16x16x32_bf16 v[44:47], v[152:155], v[160:163], v[44:47]
	v_lshl_add_u64 v[120:121], v[120:121], 0, s[30:31]
	v_mfma_f32_16x16x32_bf16 v[40:43], v[152:155], v[164:167], v[40:43]
	v_lshl_add_u64 v[122:123], v[122:123], 0, s[30:31]
	v_mfma_f32_16x16x32_bf16 v[36:39], v[152:155], v[168:171], v[36:39]
	v_lshl_add_u64 v[124:125], v[124:125], 0, s[30:31]
	v_mfma_f32_16x16x32_bf16 v[32:35], v[152:155], v[172:175], v[32:35]
	v_lshl_add_u64 v[126:127], v[126:127], 0, s[30:31]
	v_mfma_f32_16x16x32_bf16 v[64:67], v[156:159], v[160:163], v[64:67]
	v_mfma_f32_16x16x32_bf16 v[68:71], v[156:159], v[164:167], v[68:71]
	v_mfma_f32_16x16x32_bf16 v[72:75], v[156:159], v[168:171], v[72:75]
	v_mfma_f32_16x16x32_bf16 v[76:79], v[156:159], v[172:175], v[76:79]
	s_setprio 0
	s_waitcnt lgkmcnt(0)
; DEV f32x4 mfma16(bf16x8 a, bf16x8 b, f32x4 c) { return __builtin_amdgcn_mfma_f32_16x16x32_bf16(a, b, c, 0, 0, 0); }
; template <int HOOK>
; __device__ __forceinline__ void gemm_tile(const u16* __restrict__ A, int lda, const u16* __restrict__ B, int ldb, int K, char* smem, const float* ssq = nullptr) {
;     ...
;     if (HOOK && k0 >= 512 && k0 < 768) {
; #pragma unroll
;       for (int i = 0; i < 4; i++) {
;         float t8[8];
;         unpack8(ra[i], t8);
; #pragma unroll
;         for (int e = 0; e < 8; e++) t8[e] *= rs[i];
;         ra[i] = pack8(t8);
;       }
;     }
; #pragma unroll
;     for (int i = 0; i < 4; i++) {
;       int id = tid + i * NTHR; int row = id >> 3, ch = id & 7;
;       *(u32x4*)(sA + row * 72 + ch * 8) = ra[i];
;       *(u32x4*)(sB + row * 72 + ch * 8) = rb[i];
;     }
;     __syncthreads();
;     if (k0 + 64 < K) {
; #pragma unroll
;       for (int i = 0; i < 4; i++) {
;         int id = tid + i * NTHR; int row = id >> 3, ch = id & 7;
;         ra[i] = *(const u32x4*)(A + (size_t)row * lda + k0 + 64 + ch * 8);
;         rb[i] = *(const u32x4*)(B + (size_t)row * ldb + k0 + 64 + ch * 8);
;       }
;     }
; #pragma unroll
;     for (int kk = 0; kk < 64; kk += 32) {
;       bf16x8 af[4], bfr[4];
; #pragma unroll
;       for (int i = 0; i < 4; i++) af[i] = *(const bf16x8*)(sA + (wm + i * 16 + lr) * 72 + kk + lq * 8);
; #pragma unroll
;       for (int j = 0; j < 4; j++) bfr[j] = *(const bf16x8*)(sB + (wn + j * 16 + lr) * 72 + kk + lq * 8);
;       __builtin_amdgcn_s_setprio(1);
; #pragma unroll
;       for (int i = 0; i < 4; i++)
; #pragma unroll
;         for (int j = 0; j < 4; j++) acc[i][j] = mfma16(af[i], bfr[j], acc[i][j]);
;       __builtin_amdgcn_s_setprio(0);
;     }
;   }
;   __syncthreads();
;   float* sC = (float*)smem;
; #pragma unroll
;   for (int i = 0; i < 4; i++)
; #pragma unroll
;     for (int j = 0; j < 4; j++)
; #pragma unroll
;       for (int r = 0; r < 4; r++) sC[(wm + i * 16 + lq * 4 + r) * 128 + wn + j * 16 + lr] = acc[i][j][r];
;   __syncthreads();
	v_lshlrev_b32_e32 v0, 16, v176
	v_and_b32_e32 v1, 0xffff0000, v176
	v_pk_mul_f32 v[0:1], v[96:97], v[0:1]
	v_cvt_pk_bf16_f32 v176, v0, v1
	v_lshlrev_b32_e32 v2, 16, v177
	v_and_b32_e32 v3, 0xffff0000, v177
	v_pk_mul_f32 v[2:3], v[96:97], v[2:3]
	v_cvt_pk_bf16_f32 v177, v2, v3
	v_lshlrev_b32_e32 v4, 16, v178
	v_and_b32_e32 v5, 0xffff0000, v178
	v_pk_mul_f32 v[4:5], v[96:97], v[4:5]
	v_cvt_pk_bf16_f32 v178, v4, v5
	v_lshlrev_b32_e32 v6, 16, v179
	v_and_b32_e32 v7, 0xffff0000, v179
	v_pk_mul_f32 v[6:7], v[96:97], v[6:7]
	v_cvt_pk_bf16_f32 v179, v6, v7
	v_lshlrev_b32_e32 v8, 16, v180
	v_and_b32_e32 v9, 0xffff0000, v180
	v_pk_mul_f32 v[8:9], v[98:99], v[8:9]
	v_cvt_pk_bf16_f32 v180, v8, v9
	v_lshlrev_b32_e32 v10, 16, v181
	v_and_b32_e32 v11, 0xffff0000, v181
	v_pk_mul_f32 v[10:11], v[98:99], v[10:11]
	v_cvt_pk_bf16_f32 v181, v10, v11
	v_lshlrev_b32_e32 v12, 16, v182
	v_and_b32_e32 v13, 0xffff0000, v182
	v_pk_mul_f32 v[12:13], v[98:99], v[12:13]
	v_cvt_pk_bf16_f32 v182, v12, v13
	v_lshlrev_b32_e32 v14, 16, v183
	v_and_b32_e32 v15, 0xffff0000, v183
	v_pk_mul_f32 v[14:15], v[98:99], v[14:15]
	v_cvt_pk_bf16_f32 v183, v14, v15
	v_lshlrev_b32_e32 v0, 16, v184
	v_and_b32_e32 v1, 0xffff0000, v184
	v_pk_mul_f32 v[0:1], v[100:101], v[0:1]
	v_cvt_pk_bf16_f32 v184, v0, v1
	v_lshlrev_b32_e32 v2, 16, v185
	v_and_b32_e32 v3, 0xffff0000, v185
	v_pk_mul_f32 v[2:3], v[100:101], v[2:3]
	v_cvt_pk_bf16_f32 v185, v2, v3
	v_lshlrev_b32_e32 v4, 16, v186
	v_and_b32_e32 v5, 0xffff0000, v186
	v_pk_mul_f32 v[4:5], v[100:101], v[4:5]
	v_cvt_pk_bf16_f32 v186, v4, v5
	v_lshlrev_b32_e32 v6, 16, v187
	v_and_b32_e32 v7, 0xffff0000, v187
	v_pk_mul_f32 v[6:7], v[100:101], v[6:7]
	v_cvt_pk_bf16_f32 v187, v6, v7
	v_lshlrev_b32_e32 v8, 16, v188
	v_and_b32_e32 v9, 0xffff0000, v188
	v_pk_mul_f32 v[8:9], v[102:103], v[8:9]
	v_cvt_pk_bf16_f32 v188, v8, v9
	v_lshlrev_b32_e32 v10, 16, v189
	v_and_b32_e32 v11, 0xffff0000, v189
	v_pk_mul_f32 v[10:11], v[102:103], v[10:11]
	v_cvt_pk_bf16_f32 v189, v10, v11
	v_lshlrev_b32_e32 v12, 16, v190
	v_and_b32_e32 v13, 0xffff0000, v190
	v_pk_mul_f32 v[12:13], v[102:103], v[12:13]
	v_cvt_pk_bf16_f32 v190, v12, v13
	v_lshlrev_b32_e32 v14, 16, v191
	v_and_b32_e32 v15, 0xffff0000, v191
	v_pk_mul_f32 v[14:15], v[102:103], v[14:15]
	v_cvt_pk_bf16_f32 v191, v14, v15
	s_nop 1
	s_setprio 1
	v_mfma_f32_16x16x32_bf16 v[92:95], v[176:179], v[192:195], v[92:95]
	v_mfma_f32_16x16x32_bf16 v[88:91], v[176:179], v[196:199], v[88:91]
	v_mfma_f32_16x16x32_bf16 v[84:87], v[176:179], v[200:203], v[84:87]
	v_mfma_f32_16x16x32_bf16 v[80:83], v[176:179], v[204:207], v[80:83]
	v_mfma_f32_16x16x32_bf16 v[60:63], v[180:183], v[192:195], v[60:63]
	v_mfma_f32_16x16x32_bf16 v[56:59], v[180:183], v[196:199], v[56:59]
	v_mfma_f32_16x16x32_bf16 v[52:55], v[180:183], v[200:203], v[52:55]
	v_mfma_f32_16x16x32_bf16 v[48:51], v[180:183], v[204:207], v[48:51]
	v_mfma_f32_16x16x32_bf16 v[44:47], v[184:187], v[192:195], v[44:47]
	v_mfma_f32_16x16x32_bf16 v[40:43], v[184:187], v[196:199], v[40:43]
	v_mfma_f32_16x16x32_bf16 v[36:39], v[184:187], v[200:203], v[36:39]
	v_mfma_f32_16x16x32_bf16 v[32:35], v[184:187], v[204:207], v[32:35]
	v_mfma_f32_16x16x32_bf16 v[64:67], v[188:191], v[192:195], v[64:67]
	v_mfma_f32_16x16x32_bf16 v[68:71], v[188:191], v[196:199], v[68:71]
	v_mfma_f32_16x16x32_bf16 v[72:75], v[188:191], v[200:203], v[72:75]
	v_mfma_f32_16x16x32_bf16 v[76:79], v[188:191], v[204:207], v[76:79]
	s_setprio 0
.Ldp5_oe:
	s_waitcnt vmcnt(0)
	s_barrier
	s_cmpk_lt_u32 s6, 0x400
	s_cbranch_scc1 .Ldp5_loop
.LBB0_811:
	s_waitcnt vmcnt(4)
	v_lshlrev_b32_e32 v1, 9, v141
	v_and_or_b32 v0, v135, 64, v140
	v_lshl_or_b32 v1, v142, 11, v1
	v_lshl_or_b32 v0, v0, 2, v1
	v_add_u32_e32 v1, 0x400, v0
	s_barrier
	ds_write2_b32 v0, v92, v88 offset1:16
	ds_write2_b32 v0, v93, v89 offset0:128 offset1:144
	ds_write2_b32 v1, v94, v90 offset1:16
	ds_write2_b32 v1, v95, v91 offset0:128 offset1:144
	ds_write2_b32 v0, v84, v80 offset0:32 offset1:48
	ds_write2_b32 v0, v85, v81 offset0:160 offset1:176
	ds_write2_b32 v1, v86, v82 offset0:32 offset1:48
	ds_write2_b32 v1, v87, v83 offset0:160 offset1:176
	v_add_u32_e32 v1, 0x2000, v0
	v_add_u32_e32 v2, 0x2400, v0
	ds_write2_b32 v1, v60, v56 offset1:16
	ds_write2_b32 v1, v61, v57 offset0:128 offset1:144
	ds_write2_b32 v2, v62, v58 offset1:16
	ds_write2_b32 v2, v63, v59 offset0:128 offset1:144
	ds_write2_b32 v1, v52, v48 offset0:32 offset1:48
	ds_write2_b32 v1, v53, v49 offset0:160 offset1:176
	ds_write2_b32 v2, v54, v50 offset0:32 offset1:48
	ds_write2_b32 v2, v55, v51 offset0:160 offset1:176
	v_add_u32_e32 v1, 0x4000, v0
	v_add_u32_e32 v2, 0x4400, v0
	ds_write2_b32 v1, v44, v40 offset1:16
	ds_write2_b32 v1, v45, v41 offset0:128 offset1:144
	ds_write2_b32 v2, v46, v42 offset1:16
	ds_write2_b32 v2, v47, v43 offset0:128 offset1:144
	ds_write2_b32 v1, v36, v32 offset0:32 offset1:48
	ds_write2_b32 v1, v37, v33 offset0:160 offset1:176
	ds_write2_b32 v2, v38, v34 offset0:32 offset1:48
	ds_write2_b32 v2, v39, v35 offset0:160 offset1:176
	v_add_u32_e32 v1, 0x6000, v0
	v_add_u32_e32 v0, 0x6400, v0
	ds_write2_b32 v1, v64, v68 offset1:16
	ds_write2_b32 v1, v65, v69 offset0:128 offset1:144
	ds_write2_b32 v0, v66, v70 offset1:16
	ds_write2_b32 v0, v67, v71 offset0:128 offset1:144
	ds_write2_b32 v1, v72, v76 offset0:32 offset1:48
	ds_write2_b32 v1, v73, v77 offset0:160 offset1:176
	ds_write2_b32 v0, v74, v78 offset0:32 offset1:48
	ds_write2_b32 v0, v75, v79 offset0:160 offset1:176
	s_waitcnt lgkmcnt(0)
	s_barrier
	s_and_saveexec_b64 s[6:7], s[4:5]
	s_movk_i32 s13, 0x2000
	s_mov_b32 s16, 0x3fd744fd
	s_mov_b64 s[38:39], 0x2000
	s_cbranch_execz .LBB0_804
;     ...
;     } else if (EPI == EPI_OUT) {
;       float* xc = (float*)(p.ws + zz + O_XCUR);
;       const float* MOD = (const float*)(p.ws + zz + O_MOD);
; #pragma unroll 1
;       for (int i0 = tid; i0 < 128 * 32; i0 += 4 * NTHR) {
;         float4 xv4[4], gg4[4];
; #pragma unroll
;         for (int u = 0; u < 4; u++) {
;           int i = i0 + u * NTHR; int r = i >> 5, c4 = (i & 31) * 4; int row = m0 + r;
;           gg4[u] = *(const float4*)(MOD + (size_t)(l * 9 + modrow_of(row)) * 6144 + 2 * 1024 + n0 + c4);
;           xv4[u] = *(const float4*)(xc + (size_t)row * 1024 + n0 + c4);
;         }
; #pragma unroll
;         for (int u = 0; u < 4; u++) {
;           int i = i0 + u * NTHR; int r = i >> 5, c4 = (i & 31) * 4; int row = m0 + r;
;           float4 v = *(const float4*)(sC + r * 128 + c4);
;           float4 xv = xv4[u], gg = gg4[u];
;           xv.x = ALPHA * xv.x + gg.x * v.x; xv.y = ALPHA * xv.y + gg.y * v.y;
;           xv.z = ALPHA * xv.z + gg.z * v.z; xv.w = ALPHA * xv.w + gg.w * v.w;
;           *(float4*)(xc + (size_t)row * 1024 + n0 + c4) = xv;
;         }
;       }
	s_lshl_b64 s[8:9], s[14:15], 2
	s_add_u32 s10, s26, s8
	s_addc_u32 s11, s27, s9
	s_min_i32 s0, s12, 0x4000
	s_ashr_i32 s0, s0, 11
	s_add_i32 s0, s0, s28
	s_mul_i32 s0, s0, 0x6000
	s_add_u32 s38, s2, s0
	s_addc_u32 s39, s3, 0
	s_add_u32 s38, s38, s8
	s_addc_u32 s39, s39, s9
	s_add_u32 s38, s38, 0x2000
	s_addc_u32 s39, s39, 0
	v_lshlrev_b32_e32 v0, 4, v129
	v_and_b32_e32 v0, 0x1f0, v0
	global_load_dwordx4 v[4:7], v0, s[38:39]
	v_lshrrev_b32_e32 v3, 5, v129
	v_lshl_or_b32 v2, v3, 9, v0
	v_add_u32_e32 v3, s12, v3
	v_lshl_add_u32 v3, v3, 12, v0
	v_mov_b32_e32 v8, v3
	global_load_dwordx4 v[32:35], v3, s[10:11]
	v_add_u32_e32 v3, 0x8000, v3
	global_load_dwordx4 v[36:39], v3, s[10:11]
	v_add_u32_e32 v3, 0x8000, v3
	global_load_dwordx4 v[40:43], v3, s[10:11]
	v_add_u32_e32 v3, 0x8000, v3
	global_load_dwordx4 v[44:47], v3, s[10:11]
	v_add_u32_e32 v3, 0x8000, v3
	global_load_dwordx4 v[48:51], v3, s[10:11]
	v_add_u32_e32 v3, 0x8000, v3
	global_load_dwordx4 v[52:55], v3, s[10:11]
	v_add_u32_e32 v3, 0x8000, v3
	global_load_dwordx4 v[56:59], v3, s[10:11]
	v_add_u32_e32 v3, 0x8000, v3
	global_load_dwordx4 v[60:63], v3, s[10:11]
	v_add_u32_e32 v3, 0x8000, v3
	global_load_dwordx4 v[64:67], v3, s[10:11]
	v_add_u32_e32 v3, 0x8000, v3
	global_load_dwordx4 v[68:71], v3, s[10:11]
	v_add_u32_e32 v3, 0x8000, v3
	global_load_dwordx4 v[72:75], v3, s[10:11]
	v_add_u32_e32 v3, 0x8000, v3
	global_load_dwordx4 v[76:79], v3, s[10:11]
	v_add_u32_e32 v3, 0x8000, v3
	global_load_dwordx4 v[80:83], v3, s[10:11]
	v_add_u32_e32 v3, 0x8000, v3
	global_load_dwordx4 v[84:87], v3, s[10:11]
	v_add_u32_e32 v3, 0x8000, v3
	global_load_dwordx4 v[88:91], v3, s[10:11]
	v_add_u32_e32 v3, 0x8000, v3
	global_load_dwordx4 v[92:95], v3, s[10:11]
	ds_read_b128 v[144:147], v2 offset:0
	ds_read_b128 v[148:151], v2 offset:4096
	ds_read_b128 v[152:155], v2 offset:8192
	ds_read_b128 v[156:159], v2 offset:12288
	ds_read_b128 v[160:163], v2 offset:16384
	ds_read_b128 v[164:167], v2 offset:20480
	ds_read_b128 v[168:171], v2 offset:24576
	ds_read_b128 v[172:175], v2 offset:28672
	s_waitcnt vmcnt(15) lgkmcnt(7)
	v_pk_mul_f32 v[20:21], v[4:5], v[144:145]
	v_pk_mul_f32 v[22:23], v[6:7], v[146:147]
	v_pk_fma_f32 v[32:33], v[32:33], s[16:17], v[20:21] op_sel_hi:[1,0,1]
	v_pk_fma_f32 v[34:35], v[34:35], s[16:17], v[22:23] op_sel_hi:[1,0,1]
	global_store_dwordx4 v8, v[32:35], s[10:11]
	v_add_u32_e32 v8, 0x8000, v8
	ds_read_b128 v[176:179], v2 offset:32768
	s_waitcnt vmcnt(15) lgkmcnt(7)
	v_pk_mul_f32 v[20:21], v[4:5], v[148:149]
	v_pk_mul_f32 v[22:23], v[6:7], v[150:151]
	v_pk_fma_f32 v[36:37], v[36:37], s[16:17], v[20:21] op_sel_hi:[1,0,1]
	v_pk_fma_f32 v[38:39], v[38:39], s[16:17], v[22:23] op_sel_hi:[1,0,1]
	global_store_dwordx4 v8, v[36:39], s[10:11]
	v_add_u32_e32 v8, 0x8000, v8
	ds_read_b128 v[180:183], v2 offset:36864
	s_waitcnt vmcnt(15) lgkmcnt(7)
	v_pk_mul_f32 v[20:21], v[4:5], v[152:153]
	v_pk_mul_f32 v[22:23], v[6:7], v[154:155]
	v_pk_fma_f32 v[40:41], v[40:41], s[16:17], v[20:21] op_sel_hi:[1,0,1]
	v_pk_fma_f32 v[42:43], v[42:43], s[16:17], v[22:23] op_sel_hi:[1,0,1]
	global_store_dwordx4 v8, v[40:43], s[10:11]
	v_add_u32_e32 v8, 0x8000, v8
	ds_read_b128 v[184:187], v2 offset:40960
	s_waitcnt vmcnt(15) lgkmcnt(7)
	v_pk_mul_f32 v[20:21], v[4:5], v[156:157]
	v_pk_mul_f32 v[22:23], v[6:7], v[158:159]
	v_pk_fma_f32 v[44:45], v[44:45], s[16:17], v[20:21] op_sel_hi:[1,0,1]
	v_pk_fma_f32 v[46:47], v[46:47], s[16:17], v[22:23] op_sel_hi:[1,0,1]
	global_store_dwordx4 v8, v[44:47], s[10:11]
	v_add_u32_e32 v8, 0x8000, v8
	ds_read_b128 v[188:191], v2 offset:45056
	s_waitcnt vmcnt(15) lgkmcnt(7)
	v_pk_mul_f32 v[20:21], v[4:5], v[160:161]
	v_pk_mul_f32 v[22:23], v[6:7], v[162:163]
	v_pk_fma_f32 v[48:49], v[48:49], s[16:17], v[20:21] op_sel_hi:[1,0,1]
	v_pk_fma_f32 v[50:51], v[50:51], s[16:17], v[22:23] op_sel_hi:[1,0,1]
	global_store_dwordx4 v8, v[48:51], s[10:11]
	v_add_u32_e32 v8, 0x8000, v8
	ds_read_b128 v[192:195], v2 offset:49152
	s_waitcnt vmcnt(15) lgkmcnt(7)
;     ...
;       for (int i0 = tid; i0 < 128 * 32; i0 += 4 * NTHR) {
;         float4 xv4[4], gg4[4];
; #pragma unroll
;         for (int u = 0; u < 4; u++) {
;           int i = i0 + u * NTHR; int r = i >> 5, c4 = (i & 31) * 4; int row = m0 + r;
;           gg4[u] = *(const float4*)(MOD + (size_t)(l * 9 + modrow_of(row)) * 6144 + 2 * 1024 + n0 + c4);
;           xv4[u] = *(const float4*)(xc + (size_t)row * 1024 + n0 + c4);
;         }
; #pragma unroll
;         for (int u = 0; u < 4; u++) {
;           int i = i0 + u * NTHR; int r = i >> 5, c4 = (i & 31) * 4; int row = m0 + r;
;           float4 v = *(const float4*)(sC + r * 128 + c4);
;           float4 xv = xv4[u], gg = gg4[u];
;           xv.x = ALPHA * xv.x + gg.x * v.x; xv.y = ALPHA * xv.y + gg.y * v.y;
;           xv.z = ALPHA * xv.z + gg.z * v.z; xv.w = ALPHA * xv.w + gg.w * v.w;
;           *(float4*)(xc + (size_t)row * 1024 + n0 + c4) = xv;
;         }
;       }
	v_pk_mul_f32 v[20:21], v[4:5], v[164:165]
	v_pk_mul_f32 v[22:23], v[6:7], v[166:167]
	v_pk_fma_f32 v[52:53], v[52:53], s[16:17], v[20:21] op_sel_hi:[1,0,1]
	v_pk_fma_f32 v[54:55], v[54:55], s[16:17], v[22:23] op_sel_hi:[1,0,1]
	global_store_dwordx4 v8, v[52:55], s[10:11]
	v_add_u32_e32 v8, 0x8000, v8
	ds_read_b128 v[196:199], v2 offset:53248
	s_waitcnt vmcnt(15) lgkmcnt(7)
	v_pk_mul_f32 v[20:21], v[4:5], v[168:169]
	v_pk_mul_f32 v[22:23], v[6:7], v[170:171]
	v_pk_fma_f32 v[56:57], v[56:57], s[16:17], v[20:21] op_sel_hi:[1,0,1]
	v_pk_fma_f32 v[58:59], v[58:59], s[16:17], v[22:23] op_sel_hi:[1,0,1]
	global_store_dwordx4 v8, v[56:59], s[10:11]
	v_add_u32_e32 v8, 0x8000, v8
	ds_read_b128 v[200:203], v2 offset:57344
	s_waitcnt vmcnt(15) lgkmcnt(7)
	v_pk_mul_f32 v[20:21], v[4:5], v[172:173]
	v_pk_mul_f32 v[22:23], v[6:7], v[174:175]
	v_pk_fma_f32 v[60:61], v[60:61], s[16:17], v[20:21] op_sel_hi:[1,0,1]
	v_pk_fma_f32 v[62:63], v[62:63], s[16:17], v[22:23] op_sel_hi:[1,0,1]
	global_store_dwordx4 v8, v[60:63], s[10:11]
	v_add_u32_e32 v8, 0x8000, v8
	ds_read_b128 v[204:207], v2 offset:61440
	s_waitcnt vmcnt(15) lgkmcnt(7)
	v_pk_mul_f32 v[20:21], v[4:5], v[176:177]
	v_pk_mul_f32 v[22:23], v[6:7], v[178:179]
	v_pk_fma_f32 v[64:65], v[64:65], s[16:17], v[20:21] op_sel_hi:[1,0,1]
	v_pk_fma_f32 v[66:67], v[66:67], s[16:17], v[22:23] op_sel_hi:[1,0,1]
	global_store_dwordx4 v8, v[64:67], s[10:11]
	v_add_u32_e32 v8, 0x8000, v8
	s_waitcnt vmcnt(15) lgkmcnt(6)
	v_pk_mul_f32 v[20:21], v[4:5], v[180:181]
	v_pk_mul_f32 v[22:23], v[6:7], v[182:183]
	v_pk_fma_f32 v[68:69], v[68:69], s[16:17], v[20:21] op_sel_hi:[1,0,1]
	v_pk_fma_f32 v[70:71], v[70:71], s[16:17], v[22:23] op_sel_hi:[1,0,1]
	global_store_dwordx4 v8, v[68:71], s[10:11]
	v_add_u32_e32 v8, 0x8000, v8
	s_waitcnt vmcnt(15) lgkmcnt(5)
	v_pk_mul_f32 v[20:21], v[4:5], v[184:185]
	v_pk_mul_f32 v[22:23], v[6:7], v[186:187]
	v_pk_fma_f32 v[72:73], v[72:73], s[16:17], v[20:21] op_sel_hi:[1,0,1]
	v_pk_fma_f32 v[74:75], v[74:75], s[16:17], v[22:23] op_sel_hi:[1,0,1]
	global_store_dwordx4 v8, v[72:75], s[10:11]
	v_add_u32_e32 v8, 0x8000, v8
	s_waitcnt vmcnt(15) lgkmcnt(4)
	v_pk_mul_f32 v[20:21], v[4:5], v[188:189]
	v_pk_mul_f32 v[22:23], v[6:7], v[190:191]
	v_pk_fma_f32 v[76:77], v[76:77], s[16:17], v[20:21] op_sel_hi:[1,0,1]
	v_pk_fma_f32 v[78:79], v[78:79], s[16:17], v[22:23] op_sel_hi:[1,0,1]
	global_store_dwordx4 v8, v[76:79], s[10:11]
	v_add_u32_e32 v8, 0x8000, v8
	s_waitcnt vmcnt(15) lgkmcnt(3)
	v_pk_mul_f32 v[20:21], v[4:5], v[192:193]
	v_pk_mul_f32 v[22:23], v[6:7], v[194:195]
	v_pk_fma_f32 v[80:81], v[80:81], s[16:17], v[20:21] op_sel_hi:[1,0,1]
	v_pk_fma_f32 v[82:83], v[82:83], s[16:17], v[22:23] op_sel_hi:[1,0,1]
	global_store_dwordx4 v8, v[80:83], s[10:11]
	v_add_u32_e32 v8, 0x8000, v8
	s_waitcnt vmcnt(15) lgkmcnt(2)
	v_pk_mul_f32 v[20:21], v[4:5], v[196:197]
	v_pk_mul_f32 v[22:23], v[6:7], v[198:199]
	v_pk_fma_f32 v[84:85], v[84:85], s[16:17], v[20:21] op_sel_hi:[1,0,1]
	v_pk_fma_f32 v[86:87], v[86:87], s[16:17], v[22:23] op_sel_hi:[1,0,1]
	global_store_dwordx4 v8, v[84:87], s[10:11]
	v_add_u32_e32 v8, 0x8000, v8
	s_waitcnt vmcnt(15) lgkmcnt(1)
	v_pk_mul_f32 v[20:21], v[4:5], v[200:201]
	v_pk_mul_f32 v[22:23], v[6:7], v[202:203]
	v_pk_fma_f32 v[88:89], v[88:89], s[16:17], v[20:21] op_sel_hi:[1,0,1]
	v_pk_fma_f32 v[90:91], v[90:91], s[16:17], v[22:23] op_sel_hi:[1,0,1]
	global_store_dwordx4 v8, v[88:91], s[10:11]
	v_add_u32_e32 v8, 0x8000, v8
	s_waitcnt vmcnt(15) lgkmcnt(0)
	v_pk_mul_f32 v[20:21], v[4:5], v[204:205]
	v_pk_mul_f32 v[22:23], v[6:7], v[206:207]
	v_pk_fma_f32 v[92:93], v[92:93], s[16:17], v[20:21] op_sel_hi:[1,0,1]
	v_pk_fma_f32 v[94:95], v[94:95], s[16:17], v[22:23] op_sel_hi:[1,0,1]
	global_store_dwordx4 v8, v[92:95], s[10:11]
	s_branch .LBB0_804

; template <int HOOK>
; __device__ __forceinline__ void gemm_tile(const u16* __restrict__ A, int lda, const u16* __restrict__ B, int ldb, int K, char* smem, const float* ssq = nullptr) {
;     ...
;   u16* sA = (u16*)smem;
;   u16* sB = sA + 128 * 72;
;   const int tid = (threadIdx.x + zz), lane = tid & 63, wave = tid >> 6;
;   const int wm = (wave >> 1) * 64, wn = (wave & 1) * 64;
;   const int lr = lane & 15, lq = lane >> 4;
;   f32x4 acc[4][4];
; #pragma unroll
;   for (int i = 0; i < 4; i++)
; #pragma unroll
;     for (int j = 0; j < 4; j++) acc[i][j] = (f32x4){0.f, 0.f, 0.f, 0.f};
;   u32x4 ra[4], rb[4];
;   float rs[4];
;   if (HOOK) {
; #pragma unroll
;     for (int i = 0; i < 4; i++) {
;       int row = (tid + i * NTHR) >> 3;
;       float4 q = *(const float4*)(ssq + (size_t)row * 4);
;       rs[i] = rsqrtf((q.x + q.y + q.z + q.w) * (1.f / 256.f) + 1e-6f);
;     }
;   }
; #pragma unroll
;   for (int i = 0; i < 4; i++) {
;     int id = tid + i * NTHR; int row = id >> 3, ch = id & 7;
;     ra[i] = *(const u32x4*)(A + (size_t)row * lda + ch * 8);
;     rb[i] = *(const u32x4*)(B + (size_t)row * ldb + ch * 8);
;   }
; #pragma unroll 1
;   for (int k0 = 0; k0 < K; k0 += 64) {
;     __syncthreads();
;     ...
;     int mt = t / ntiles, nt = t % ntiles;
;     int m0 = mt * 128, n0 = nt * 128;
;     gemm_tile<(EPI == EPI_OUT) ? 1 : 0>(A + (size_t)m0 * lda, lda, Bt + (size_t)n0 * ldb, ldb, K, smem, (const float*)(p.ws + zz + O_SSQ) + (size_t)m0 * 4);
.LBB0_1458:
	s_mul_hi_i32 s0, s10, 0x2aaaaaab
	s_lshr_b32 s1, s0, 31
	s_ashr_i32 s0, s0, 2
	s_add_i32 s0, s0, s1
	s_mul_i32 s1, s0, 24
	s_lshl_b32 s2, s0, 7
	s_sub_i32 s1, s10, s1
	s_ashr_i32 s3, s2, 31
	s_lshl_b32 s6, s1, 7
	s_lshl_b64 s[0:1], s[2:3], 11
	s_add_u32 s8, s11, s0
	s_addc_u32 s9, s12, s1
	s_ashr_i32 s7, s6, 31
	s_mov_b32 s3, 0
	s_lshl_b64 s[22:23], s[6:7], 11
	v_add_u32_e32 v122, s3, v128
	s_waitcnt vmcnt(3)
	v_add_u32_e32 v8, 0x100, v122
	s_waitcnt vmcnt(2)
	v_add_u32_e32 v16, 0x200, v122
	s_waitcnt vmcnt(0)
	v_add_u32_e32 v28, 0x300, v122
	s_add_u32 s24, s13, s22
	v_lshlrev_b32_e32 v0, 4, v122
	v_ashrrev_i32_e32 v36, 3, v122
	v_ashrrev_i32_e32 v40, 3, v8
	v_ashrrev_i32_e32 v44, 3, v16
	v_ashrrev_i32_e32 v48, 3, v28
	s_addc_u32 s25, s14, s23
	v_and_b32_e32 v132, 0x70, v0
	v_ashrrev_i32_e32 v37, 31, v36
	v_ashrrev_i32_e32 v41, 31, v40
	v_ashrrev_i32_e32 v45, 31, v44
	v_ashrrev_i32_e32 v49, 31, v48
	v_lshl_add_u64 v[24:25], s[8:9], 0, v[132:133]
	v_lshl_add_u64 v[26:27], s[24:25], 0, v[132:133]
	v_lshlrev_b64 v[38:39], 11, v[36:37]
	v_lshlrev_b64 v[42:43], 11, v[40:41]
	v_lshlrev_b64 v[46:47], 11, v[44:45]
	v_lshlrev_b64 v[50:51], 11, v[48:49]
	v_lshl_add_u64 v[0:1], v[24:25], 0, v[38:39]
	v_lshl_add_u64 v[4:5], v[26:27], 0, v[38:39]
	v_lshl_add_u64 v[8:9], v[24:25], 0, v[42:43]
	v_lshl_add_u64 v[12:13], v[26:27], 0, v[42:43]
	v_lshl_add_u64 v[16:17], v[24:25], 0, v[46:47]
	v_lshl_add_u64 v[20:21], v[26:27], 0, v[46:47]
	v_lshl_add_u64 v[24:25], v[24:25], 0, v[50:51]
	v_lshl_add_u64 v[26:27], v[26:27], 0, v[50:51]
	v_ashrrev_i32_e32 v52, 1, v122
	v_and_b32_e32 v123, 15, v122
	v_and_b32_e32 v124, 0xffffffc0, v52
	s_add_u32 s0, s18, s0
	v_or_b32_e32 v24, v124, v123
	s_addc_u32 s1, s19, s1
	v_bfe_u32 v125, v122, 4, 2
	v_and_b32_e32 v26, 0x4f, v122
	v_mul_lo_u32 v27, v24, s33
	v_and_b32_e32 v24, 7, v122
	v_lshl_add_u64 v[104:105], s[0:1], 0, v[38:39]
	v_lshl_add_u64 v[106:107], s[0:1], 0, v[42:43]
	v_lshl_add_u64 v[108:109], s[0:1], 0, v[46:47]
	v_lshl_add_u64 v[110:111], s[0:1], 0, v[50:51]
	s_add_u32 s0, s20, s22
	v_lshlrev_b32_e32 v25, 4, v125
	v_mad_u64_u32 v[96:97], s[8:9], v36, s33, v[132:133]
	v_mad_u64_u32 v[98:99], s[8:9], v40, s33, v[132:133]
	v_mad_u64_u32 v[100:101], s[8:9], v44, s33, v[132:133]
	v_mad_u64_u32 v[102:103], s[8:9], v48, s33, v[132:133]
	v_mul_u32_u24_e32 v26, 0x90, v26
	v_lshlrev_b32_e32 v132, 4, v24
	s_addc_u32 s1, s21, s23
	v_mov_b32_e32 v24, 0
	v_lshl_add_u64 v[112:113], s[0:1], 0, v[38:39]
	v_lshl_add_u64 v[114:115], s[0:1], 0, v[42:43]
	v_lshl_add_u64 v[116:117], s[0:1], 0, v[46:47]
	v_lshl_add_u64 v[118:119], s[0:1], 0, v[50:51]
	s_mov_b32 s3, 0
	v_add_u32_e32 v97, v25, v27
	v_add_u32_e32 v99, v25, v26
	v_mov_b32_e32 v25, v24
	v_mov_b32_e32 v26, v24
	v_mov_b32_e32 v27, v24
	v_mov_b32_e32 v36, v24
	v_mov_b32_e32 v37, v24
	v_mov_b32_e32 v38, v24
	v_mov_b32_e32 v39, v24
	v_mov_b32_e32 v40, v24
	v_mov_b32_e32 v41, v24
	v_mov_b32_e32 v42, v24
	v_mov_b32_e32 v43, v24
	v_mov_b32_e32 v44, v24
	v_mov_b32_e32 v45, v24
	v_mov_b32_e32 v46, v24
	v_mov_b32_e32 v47, v24
	v_mov_b32_e32 v48, v24
	v_mov_b32_e32 v49, v24
	v_mov_b32_e32 v50, v24
	v_mov_b32_e32 v51, v24
	v_mov_b32_e32 v52, v24
	v_mov_b32_e32 v53, v24
	v_mov_b32_e32 v54, v24
	v_mov_b32_e32 v55, v24
	v_mov_b32_e32 v56, v24
	v_mov_b32_e32 v57, v24
	v_mov_b32_e32 v58, v24
	v_mov_b32_e32 v59, v24
	v_mov_b32_e32 v60, v24
	v_mov_b32_e32 v61, v24
	v_mov_b32_e32 v62, v24
	v_mov_b32_e32 v63, v24
	v_mov_b32_e32 v64, v24
	v_mov_b32_e32 v65, v24
	v_mov_b32_e32 v66, v24
	v_mov_b32_e32 v67, v24
	v_mov_b32_e32 v68, v24
	v_mov_b32_e32 v69, v24
	v_mov_b32_e32 v70, v24
	v_mov_b32_e32 v71, v24
	v_mov_b32_e32 v72, v24
	v_mov_b32_e32 v73, v24
	v_mov_b32_e32 v74, v24
	v_mov_b32_e32 v75, v24
	v_mov_b32_e32 v76, v24
	v_mov_b32_e32 v77, v24
	v_mov_b32_e32 v78, v24
	v_mov_b32_e32 v79, v24
	v_mov_b32_e32 v80, v24
	v_mov_b32_e32 v81, v24
	v_mov_b32_e32 v82, v24
	v_mov_b32_e32 v83, v24
	v_mov_b32_e32 v84, v24
	v_mov_b32_e32 v85, v24
	v_mov_b32_e32 v86, v24
	v_mov_b32_e32 v87, v24
	v_mov_b32_e32 v88, v24
	v_mov_b32_e32 v89, v24
	v_mov_b32_e32 v90, v24
	v_mov_b32_e32 v91, v24
	v_mov_b32_e32 v92, v24
	v_mov_b32_e32 v93, v24
	v_mov_b32_e32 v94, v24
	v_mov_b32_e32 v95, v24
	v_lshrrev_b32_e32 v208, 3, v122
	v_xor_b32_e32 v208, v208, v122
	v_and_b32_e32 v208, 7, v208
	v_lshlrev_b32_e32 v208, 4, v208
	v_add_u32_e32 v208, 0xffffff80, v208
	v_mov_b32_e32 v209, -1
	v_lshl_add_u64 v[104:105], v[104:105], 0, v[208:209]
	v_lshl_add_u64 v[106:107], v[106:107], 0, v[208:209]
	v_lshl_add_u64 v[108:109], v[108:109], 0, v[208:209]
	v_lshl_add_u64 v[110:111], v[110:111], 0, v[208:209]
	v_lshl_add_u64 v[112:113], v[112:113], 0, v[208:209]
	v_lshl_add_u64 v[114:115], v[114:115], 0, v[208:209]
	v_lshl_add_u64 v[116:117], v[116:117], 0, v[208:209]
	v_lshl_add_u64 v[118:119], v[118:119], 0, v[208:209]
	v_lshrrev_b32_e32 v208, 6, v122
	s_nop 1
	v_readfirstlane_b32 s56, v208
	s_nop 3
	s_lshl_b32 s56, s56, 10
	s_waitcnt lgkmcnt(0)
	s_barrier
	s_mov_b32 m0, s56
	s_nop 0
	global_load_lds_dwordx4 v[104:105], off
	s_add_u32 m0, s56, 0x1000
	s_nop 0
	global_load_lds_dwordx4 v[106:107], off
	s_add_u32 m0, s56, 0x2000
	s_nop 0
	global_load_lds_dwordx4 v[108:109], off
	s_add_u32 m0, s56, 0x3000
	s_nop 0
	global_load_lds_dwordx4 v[110:111], off
	s_add_u32 m0, s56, 0x4000
	s_nop 0
	global_load_lds_dwordx4 v[112:113], off
	s_add_u32 m0, s56, 0x5000
	s_nop 0
	global_load_lds_dwordx4 v[114:115], off
	s_add_u32 m0, s56, 0x6000
	s_nop 0
	global_load_lds_dwordx4 v[116:117], off
	s_add_u32 m0, s56, 0x7000
	s_nop 0
	global_load_lds_dwordx4 v[118:119], off
	v_lshl_add_u64 v[104:105], v[104:105], 0, s[30:31]
	v_lshl_add_u64 v[106:107], v[106:107], 0, s[30:31]
	v_lshl_add_u64 v[108:109], v[108:109], 0, s[30:31]
	v_lshl_add_u64 v[110:111], v[110:111], 0, s[30:31]
	v_lshl_add_u64 v[112:113], v[112:113], 0, s[30:31]
	v_lshl_add_u64 v[114:115], v[114:115], 0, s[30:31]
	v_lshl_add_u64 v[116:117], v[116:117], 0, s[30:31]
	v_lshl_add_u64 v[118:119], v[118:119], 0, s[30:31]
	v_and_b32_e32 v204, 7, v123
	v_xor_b32_e32 v204, v204, v125
	v_lshlrev_b32_e32 v204, 4, v204
	v_or_b32_e32 v206, v124, v123
	v_lshl_add_u32 v205, v206, 7, v204
	v_and_b32_e32 v206, 0x4f, v122
	v_lshl_add_u32 v206, v206, 7, v204
	v_xor_b32_e32 v207, 64, v206
	v_xor_b32_e32 v204, 64, v205
	s_waitcnt vmcnt(0)
	s_barrier

; template <int HOOK>
; __device__ __forceinline__ void gemm_tile(const u16* __restrict__ A, int lda, const u16* __restrict__ B, int ldb, int K, char* smem, const float* ssq = nullptr) {
;     ...
;   __syncthreads();
;   float* sC = (float*)smem;
; #pragma unroll
;   for (int i = 0; i < 4; i++)
; #pragma unroll
;     for (int j = 0; j < 4; j++)
; #pragma unroll
;       for (int r = 0; r < 4; r++) sC[(wm + i * 16 + lq * 4 + r) * 128 + wn + j * 16 + lr] = acc[i][j][r];
;   __syncthreads();
;     ...
;     if (EPI == EPI_BF16) {
;       u16* out = (u16*)outp;
;       for (int i = tid; i < 128 * 32; i += NTHR) {
;         int r = i >> 5, c4 = (i & 31) * 4;
;         float4 v = *(const float4*)(sC + r * 128 + c4);
;         uint2 o; o.x = pack2(v.x, v.y); o.y = pack2(v.z, v.w);
;         *(uint2*)(out + (size_t)(m0 + r) * ldo + n0 + c4) = o;
;       }
.LBB0_1462:
	s_waitcnt vmcnt(7)
	v_lshlrev_b32_e32 v1, 9, v124
	v_and_or_b32 v0, v122, 64, v123
	v_lshl_or_b32 v1, v125, 11, v1
	v_lshl_or_b32 v0, v0, 2, v1
	v_add_u32_e32 v1, 0x400, v0
	s_barrier
	ds_write2_b32 v0, v92, v88 offset1:16
	ds_write2_b32 v0, v93, v89 offset0:128 offset1:144
	ds_write2_b32 v1, v94, v90 offset1:16
	ds_write2_b32 v1, v95, v91 offset0:128 offset1:144
	ds_write2_b32 v0, v84, v80 offset0:32 offset1:48
	ds_write2_b32 v0, v85, v81 offset0:160 offset1:176
	ds_write2_b32 v1, v86, v82 offset0:32 offset1:48
	ds_write2_b32 v1, v87, v83 offset0:160 offset1:176
	v_add_u32_e32 v1, 0x2000, v0
	v_add_u32_e32 v2, 0x2400, v0
	ds_write2_b32 v1, v76, v72 offset1:16
	ds_write2_b32 v1, v77, v73 offset0:128 offset1:144
	ds_write2_b32 v2, v78, v74 offset1:16
	ds_write2_b32 v2, v79, v75 offset0:128 offset1:144
	ds_write2_b32 v1, v68, v64 offset0:32 offset1:48
	ds_write2_b32 v1, v69, v65 offset0:160 offset1:176
	ds_write2_b32 v2, v70, v66 offset0:32 offset1:48
	ds_write2_b32 v2, v71, v67 offset0:160 offset1:176
	v_add_u32_e32 v1, 0x4000, v0
	v_add_u32_e32 v2, 0x4400, v0
	ds_write2_b32 v1, v60, v56 offset1:16
	ds_write2_b32 v1, v61, v57 offset0:128 offset1:144
	ds_write2_b32 v2, v62, v58 offset1:16
	ds_write2_b32 v2, v63, v59 offset0:128 offset1:144
	ds_write2_b32 v1, v52, v48 offset0:32 offset1:48
	ds_write2_b32 v1, v53, v49 offset0:160 offset1:176
	ds_write2_b32 v2, v54, v50 offset0:32 offset1:48
	ds_write2_b32 v2, v55, v51 offset0:160 offset1:176
	v_add_u32_e32 v1, 0x6000, v0
	v_add_u32_e32 v0, 0x6400, v0
	ds_write2_b32 v1, v44, v40 offset1:16
	ds_write2_b32 v1, v45, v41 offset0:128 offset1:144
	ds_write2_b32 v0, v46, v42 offset1:16
	ds_write2_b32 v0, v47, v43 offset0:128 offset1:144
	ds_write2_b32 v1, v36, v24 offset0:32 offset1:48
	ds_write2_b32 v1, v37, v25 offset0:160 offset1:176
	ds_write2_b32 v0, v38, v26 offset0:32 offset1:48
	ds_write2_b32 v0, v39, v27 offset0:160 offset1:176
	s_waitcnt lgkmcnt(0)
	s_barrier
	s_and_saveexec_b64 s[0:1], s[4:5]
	s_movk_i32 s3, 0xeff
	s_movk_i32 s24, 0x1800
	s_cbranch_execz .LBB0_1457
	s_lshl_b64 s[6:7], s[6:7], 1
	s_add_u32 s6, s15, s6
	s_addc_u32 s7, s16, s7
	v_lshrrev_b32_e32 v6, 5, v120
	v_and_b32_e32 v7, 31, v120
	v_lshlrev_b32_e32 v0, 4, v7
	v_lshl_or_b32 v0, v6, 9, v0
	v_add_u32_e32 v6, s2, v6
	v_mul_u32_u24_e32 v6, 0x1800, v6
	v_lshl_add_u32 v1, v7, 3, v6
	ds_read_b128 v[8:11], v0 offset:0
	ds_read_b128 v[12:15], v0 offset:4096
	ds_read_b128 v[16:19], v0 offset:8192
	ds_read_b128 v[20:23], v0 offset:12288
	ds_read_b128 v[24:27], v0 offset:16384
	ds_read_b128 v[28:31], v0 offset:20480
	ds_read_b128 v[32:35], v0 offset:24576
	ds_read_b128 v[36:39], v0 offset:28672
	s_waitcnt lgkmcnt(7)
	v_cvt_pk_bf16_f32 v8, v8, v9
	v_cvt_pk_bf16_f32 v9, v10, v11
	global_store_dwordx2 v1, v[8:9], s[6:7]
	v_add_u32_e32 v1, 0xc000, v1
	ds_read_b128 v[40:43], v0 offset:32768
	s_waitcnt lgkmcnt(7)
	v_cvt_pk_bf16_f32 v12, v12, v13
	v_cvt_pk_bf16_f32 v13, v14, v15
	global_store_dwordx2 v1, v[12:13], s[6:7]
	v_add_u32_e32 v1, 0xc000, v1
	ds_read_b128 v[44:47], v0 offset:36864
	s_waitcnt lgkmcnt(7)
	v_cvt_pk_bf16_f32 v16, v16, v17
	v_cvt_pk_bf16_f32 v17, v18, v19
	global_store_dwordx2 v1, v[16:17], s[6:7]
	v_add_u32_e32 v1, 0xc000, v1
	ds_read_b128 v[48:51], v0 offset:40960
	s_waitcnt lgkmcnt(7)
	v_cvt_pk_bf16_f32 v20, v20, v21
	v_cvt_pk_bf16_f32 v21, v22, v23
	global_store_dwordx2 v1, v[20:21], s[6:7]
	v_add_u32_e32 v1, 0xc000, v1
	ds_read_b128 v[52:55], v0 offset:45056
	s_waitcnt lgkmcnt(7)
	v_cvt_pk_bf16_f32 v24, v24, v25
	v_cvt_pk_bf16_f32 v25, v26, v27
	global_store_dwordx2 v1, v[24:25], s[6:7]
	v_add_u32_e32 v1, 0xc000, v1
	ds_read_b128 v[56:59], v0 offset:49152
	s_waitcnt lgkmcnt(7)
	v_cvt_pk_bf16_f32 v28, v28, v29
	v_cvt_pk_bf16_f32 v29, v30, v31
	global_store_dwordx2 v1, v[28:29], s[6:7]
	v_add_u32_e32 v1, 0xc000, v1
	ds_read_b128 v[60:63], v0 offset:53248
	s_waitcnt lgkmcnt(7)
	v_cvt_pk_bf16_f32 v32, v32, v33
	v_cvt_pk_bf16_f32 v33, v34, v35
	global_store_dwordx2 v1, v[32:33], s[6:7]
	v_add_u32_e32 v1, 0xc000, v1
	ds_read_b128 v[64:67], v0 offset:57344
	s_waitcnt lgkmcnt(7)
	v_cvt_pk_bf16_f32 v36, v36, v37
	v_cvt_pk_bf16_f32 v37, v38, v39
	global_store_dwordx2 v1, v[36:37], s[6:7]
	v_add_u32_e32 v1, 0xc000, v1
	ds_read_b128 v[68:71], v0 offset:61440
	s_waitcnt lgkmcnt(7)
	v_cvt_pk_bf16_f32 v40, v40, v41
	v_cvt_pk_bf16_f32 v41, v42, v43
	global_store_dwordx2 v1, v[40:41], s[6:7]
	v_add_u32_e32 v1, 0xc000, v1
	s_waitcnt lgkmcnt(6)
	v_cvt_pk_bf16_f32 v44, v44, v45
	v_cvt_pk_bf16_f32 v45, v46, v47
	global_store_dwordx2 v1, v[44:45], s[6:7]
	v_add_u32_e32 v1, 0xc000, v1
	s_waitcnt lgkmcnt(5)
	v_cvt_pk_bf16_f32 v48, v48, v49
	v_cvt_pk_bf16_f32 v49, v50, v51
	global_store_dwordx2 v1, v[48:49], s[6:7]
	v_add_u32_e32 v1, 0xc000, v1
	s_waitcnt lgkmcnt(4)
	v_cvt_pk_bf16_f32 v52, v52, v53
	v_cvt_pk_bf16_f32 v53, v54, v55
	global_store_dwordx2 v1, v[52:53], s[6:7]
	v_add_u32_e32 v1, 0xc000, v1
	s_waitcnt lgkmcnt(3)
	v_cvt_pk_bf16_f32 v56, v56, v57
	v_cvt_pk_bf16_f32 v57, v58, v59
	global_store_dwordx2 v1, v[56:57], s[6:7]
	v_add_u32_e32 v1, 0xc000, v1
	s_waitcnt lgkmcnt(2)
	v_cvt_pk_bf16_f32 v60, v60, v61
	v_cvt_pk_bf16_f32 v61, v62, v63
	global_store_dwordx2 v1, v[60:61], s[6:7]
	v_add_u32_e32 v1, 0xc000, v1
	s_waitcnt lgkmcnt(1)
	v_cvt_pk_bf16_f32 v64, v64, v65
	v_cvt_pk_bf16_f32 v65, v66, v67
	global_store_dwordx2 v1, v[64:65], s[6:7]
	v_add_u32_e32 v1, 0xc000, v1
	s_waitcnt lgkmcnt(0)
	v_cvt_pk_bf16_f32 v68, v68, v69
	v_cvt_pk_bf16_f32 v69, v70, v71
	global_store_dwordx2 v1, v[68:69], s[6:7]
	s_branch .LBB0_1457
